# v17: residual GEMM epilogue - row sum-of-squares atomics of a batch issued after the next batch's loads are waited for (counted waits re-derived); on top of v16
# baseline (speedup 1.0000x reference)
;     __device__ __forceinline__ void operator()(const f32x4 (&acc)[2][2][4][2], const Unit& u, int wr, int wc, int fr, int fq) const {
;     ...
;                 u32x4 xin[2][2];
; #pragma unroll
;                 for (int mm = 0; mm < 2; ++mm)
; #pragma unroll
;                     for (int bj = 0; bj < 2; ++bj) xin[mm][bj] = *(const u32x4*)(X + (size_t)(row0 + ai * HALF + (mp * 2 + mm) * 16) * DM + col0 + bj * HALF);
;                 f32x4 pv[2][2][2];
; #pragma unroll
;                 for (int mm = 0; mm < 2; ++mm)
; #pragma unroll
;                     for (int bj = 0; bj < 2; ++bj)
; #pragma unroll
;                         for (int n = 0; n < 2; ++n) pv[mm][bj][n] = (f32x4){0.f, 0.f, 0.f, 0.f};
;                 if (src) {
;                     u32x4 pc[2][2];
;     ...
;                     asm volatile("global_load_dwordx4 %0, %4, off sc1\n\tglobal_load_dwordx4 %1, %5, off sc1\n\tglobal_load_dwordx4 %2, %6, off sc1\n\tglobal_load_dwordx4 %3, %7, off sc1\n\ts_waitcnt vmcnt(0)"
;                                  : "=&v"(pc[0][0]), "=&v"(pc[0][1]), "=&v"(pc[1][0]), "=&v"(pc[1][1])
;                                  : "v"(src + CI(0, 0)), "v"(src + CI(0, 1)), "v"(src + CI(1, 0)), "v"(src + CI(1, 1))
;                                  : "memory");
;     ...
; #pragma unroll
;                     for (int mm = 0; mm < 2; ++mm)
; #pragma unroll
;                         for (int bj = 0; bj < 2; ++bj) { float f[8]; unpack8(pc[mm][bj], f); pv[mm][bj][0] = (f32x4){f[0], f[1], f[2], f[3]}; pv[mm][bj][1] = (f32x4){f[4], f[5], f[6], f[7]}; }
;                 }
; #pragma unroll
;                 for (int mm = 0; mm < 2; ++mm) {
;                     const int m = mp * 2 + mm;
;                     const int row = row0 + ai * HALF + m * 16;
;                     float s = 0.f;
; #pragma unroll
;                     for (int bj = 0; bj < 2; ++bj) {
;                         u32x4* px = (u32x4*)(X + (size_t)row * DM + col0 + bj * HALF);
;                         float xo[8]; unpack8(xin[mm][bj], xo);
;                         const f32x4 a0 = acc[ai][bj][m][0] + pv[mm][bj][0], a1 = acc[ai][bj][m][1] + pv[mm][bj][1];
;                         u32x4 w;
;                         w.x = cvt_pk(xo[0] + scale * a0[0], xo[1] + scale * a0[1]); w.y = cvt_pk(xo[2] + scale * a0[2], xo[3] + scale * a0[3]);
.LBB0_405:
	s_or_b64 exec, exec, s[12:13]
	s_waitcnt vmcnt(0)
	v_lshlrev_b32_e32 v210, 16, v140
	v_and_b32_e32 v211, 0xffff0000, v140
	v_lshlrev_b32_e32 v214, 16, v141
	v_and_b32_e32 v215, 0xffff0000, v141
	v_and_b32_e32 v238, 0xffff0000, v142
	v_pk_add_f32 v[140:141], v[124:125], v[206:207]
	v_pk_add_f32 v[202:203], v[120:121], v[202:203]
	v_lshlrev_b32_e32 v237, 16, v142
	v_fmac_f32_e32 v210, 0.5, v140
	v_fmac_f32_e32 v211, 0.5, v141
	v_cvt_pk_bf16_f32 v140, v210, v211
	v_fmac_f32_e32 v238, 0.5, v203
	v_and_b32_e32 v203, 0xffff0000, v140
	v_lshlrev_b32_e32 v244, 16, v143
	v_and_b32_e32 v245, 0xffff0000, v143
	v_pk_add_f32 v[142:143], v[126:127], v[208:209]
	v_pk_add_f32 v[204:205], v[122:123], v[204:205]
	v_fmac_f32_e32 v237, 0.5, v202
	v_lshlrev_b32_e32 v202, 16, v140
	v_mul_f32_e32 v203, v203, v203
	v_fmac_f32_e32 v214, 0.5, v142
	v_fmac_f32_e32 v215, 0.5, v143
	v_cvt_pk_bf16_f32 v141, v214, v215
	v_fmac_f32_e32 v244, 0.5, v204
	v_lshlrev_b32_e32 v204, 16, v141
	v_fmac_f32_e32 v203, v202, v202
	v_fmac_f32_e32 v245, 0.5, v205
	v_and_b32_e32 v205, 0xffff0000, v141
	v_fmac_f32_e32 v203, v204, v204
	v_cvt_pk_bf16_f32 v142, v237, v238
	v_fmac_f32_e32 v203, v205, v205
	v_lshlrev_b32_e32 v206, 16, v142
	v_and_b32_e32 v207, 0xffff0000, v142
	v_fmac_f32_e32 v203, v206, v206
	v_cvt_pk_bf16_f32 v143, v244, v245
	v_fmac_f32_e32 v203, v207, v207
	v_lshlrev_b32_e32 v208, 16, v143
	v_and_b32_e32 v209, 0xffff0000, v143
	v_fmac_f32_e32 v203, v208, v208
	v_fmac_f32_e32 v203, v209, v209
	v_lshlrev_b32_e32 v202, 16, v136
	v_and_b32_e32 v204, 0xffff0000, v136
	v_lshlrev_b32_e32 v205, 16, v137
	v_and_b32_e32 v206, 0xffff0000, v137
	v_lshlrev_b32_e32 v207, 16, v138
	v_and_b32_e32 v208, 0xffff0000, v138
	v_lshlrev_b32_e32 v209, 16, v139
	v_and_b32_e32 v210, 0xffff0000, v139
	v_pk_add_f32 v[136:137], v[94:95], v[200:201]
	v_pk_add_f32 v[138:139], v[92:93], v[198:199]
	v_pk_add_f32 v[198:199], v[90:91], v[196:197]
	v_pk_add_f32 v[196:197], v[88:89], v[194:195]
	v_fmac_f32_e32 v202, 0.5, v138
	v_fmac_f32_e32 v204, 0.5, v139
	v_cvt_pk_bf16_f32 v194, v202, v204
	v_fmac_f32_e32 v205, 0.5, v136
	v_lshlrev_b32_e32 v136, 16, v194
	v_fmac_f32_e32 v206, 0.5, v137
	v_and_b32_e32 v137, 0xffff0000, v194
	v_fmac_f32_e32 v203, v136, v136
	v_cvt_pk_bf16_f32 v195, v205, v206
	v_fmac_f32_e32 v203, v137, v137
	v_lshlrev_b32_e32 v138, 16, v195
	v_and_b32_e32 v139, 0xffff0000, v195
	v_fmac_f32_e32 v203, v138, v138
	v_fmac_f32_e32 v207, 0.5, v196
	v_fmac_f32_e32 v208, 0.5, v197
	v_cvt_pk_bf16_f32 v196, v207, v208
	v_fmac_f32_e32 v209, 0.5, v198
	v_lshlrev_b32_e32 v198, 16, v196
	v_fmac_f32_e32 v203, v139, v139
	v_and_b32_e32 v137, 64, v221
	v_fmac_f32_e32 v210, 0.5, v199
	v_and_b32_e32 v199, 0xffff0000, v196
	v_fmac_f32_e32 v203, v198, v198
	v_xor_b32_e32 v136, 16, v221
	v_add_u32_e32 v137, 64, v137
	v_cvt_pk_bf16_f32 v197, v209, v210
	v_fmac_f32_e32 v203, v199, v199
	v_lshlrev_b32_e32 v200, 16, v197
	v_cmp_lt_i32_e64 s[12:13], v136, v137
	v_and_b32_e32 v201, 0xffff0000, v197
	v_fmac_f32_e32 v203, v200, v200
	v_cndmask_b32_e64 v136, v221, v136, s[12:13]
	v_fmac_f32_e32 v203, v201, v201
	v_lshlrev_b32_e32 v237, 2, v136
	ds_bpermute_b32 v136, v237, v203
	v_xor_b32_e32 v138, 32, v221
	v_cmp_lt_i32_e64 s[12:13], v138, v137
	s_waitcnt lgkmcnt(0)
	v_add_f32_e32 v136, v203, v136
	v_cndmask_b32_e64 v137, v221, v138, s[12:13]
	v_lshlrev_b32_e32 v238, 2, v137
	ds_bpermute_b32 v137, v238, v136
	v_lshl_add_u64 v[138:139], s[28:29], 0, v[174:175]
	v_lshl_add_u64 v[138:139], v[168:169], 1, v[138:139]
	global_store_dwordx4 v[138:139], v[140:143], off
	global_store_dwordx4 v[138:139], v[194:197], off offset:256
	s_waitcnt lgkmcnt(0)
	v_add_f32_e32 v250, v136, v137
.LBB0_407:
	v_lshlrev_b32_e32 v140, 16, v132
	v_and_b32_e32 v141, 0xffff0000, v132
	v_lshlrev_b32_e32 v142, 16, v133
	v_and_b32_e32 v143, 0xffff0000, v133
	v_and_b32_e32 v197, 0xffff0000, v135
	v_pk_add_f32 v[132:133], v[116:117], v[190:191]
	s_waitcnt lgkmcnt(0)
	v_pk_add_f32 v[136:137], v[114:115], v[188:189]
	v_lshlrev_b32_e32 v196, 16, v135
	v_fmac_f32_e32 v140, 0.5, v132
	v_fmac_f32_e32 v141, 0.5, v133
	v_cvt_pk_bf16_f32 v132, v140, v141
	v_fmac_f32_e32 v197, 0.5, v137
	v_and_b32_e32 v137, 0xffff0000, v132
	v_lshlrev_b32_e32 v194, 16, v134
	v_and_b32_e32 v195, 0xffff0000, v134
	v_pk_add_f32 v[134:135], v[118:119], v[192:193]
	v_pk_add_f32 v[138:139], v[112:113], v[186:187]
	v_fmac_f32_e32 v196, 0.5, v136
	v_lshlrev_b32_e32 v136, 16, v132
	v_mul_f32_e32 v186, v137, v137
	v_fmac_f32_e32 v142, 0.5, v134
	v_fmac_f32_e32 v143, 0.5, v135
	v_cvt_pk_bf16_f32 v133, v142, v143
	v_fmac_f32_e32 v194, 0.5, v138
	v_lshlrev_b32_e32 v138, 16, v133
	v_fmac_f32_e32 v186, v136, v136
	v_fmac_f32_e32 v195, 0.5, v139
	v_and_b32_e32 v139, 0xffff0000, v133
	v_fmac_f32_e32 v186, v138, v138
	v_cvt_pk_bf16_f32 v134, v194, v195
	v_fmac_f32_e32 v186, v139, v139
	v_lshlrev_b32_e32 v140, 16, v134
	v_and_b32_e32 v141, 0xffff0000, v134
	v_fmac_f32_e32 v186, v140, v140
	v_cvt_pk_bf16_f32 v135, v196, v197
	v_fmac_f32_e32 v186, v141, v141
	v_lshlrev_b32_e32 v142, 16, v135
	v_and_b32_e32 v143, 0xffff0000, v135
	v_fmac_f32_e32 v186, v142, v142
	v_lshlrev_b32_e32 v136, 16, v128
	v_lshlrev_b32_e32 v187, 16, v130
	v_and_b32_e32 v188, 0xffff0000, v130
	v_lshlrev_b32_e32 v189, 16, v131
	v_and_b32_e32 v190, 0xffff0000, v131
	v_pk_add_f32 v[130:131], v[84:85], v[182:183]
	v_fmac_f32_e32 v186, v143, v143
	v_and_b32_e32 v137, 0xffff0000, v128
	v_lshlrev_b32_e32 v142, 16, v129
	v_and_b32_e32 v143, 0xffff0000, v129
	v_pk_add_f32 v[128:129], v[86:87], v[184:185]
	v_fmac_f32_e32 v136, 0.5, v130
	v_fmac_f32_e32 v137, 0.5, v131
	v_cvt_pk_bf16_f32 v136, v136, v137
	v_fmac_f32_e32 v142, 0.5, v128
	v_lshlrev_b32_e32 v128, 16, v136
	v_fmac_f32_e32 v143, 0.5, v129
	v_and_b32_e32 v129, 0xffff0000, v136
	v_fmac_f32_e32 v186, v128, v128
	v_cvt_pk_bf16_f32 v137, v142, v143
	v_fmac_f32_e32 v186, v129, v129
	v_lshlrev_b32_e32 v130, 16, v137
	v_pk_add_f32 v[140:141], v[82:83], v[180:181]
	v_pk_add_f32 v[138:139], v[80:81], v[178:179]
	v_and_b32_e32 v131, 0xffff0000, v137
	v_fmac_f32_e32 v186, v130, v130
	v_fmac_f32_e32 v187, 0.5, v138
	v_fmac_f32_e32 v188, 0.5, v139
	v_cvt_pk_bf16_f32 v138, v187, v188
	v_fmac_f32_e32 v189, 0.5, v140
	v_lshlrev_b32_e32 v140, 16, v138
	v_fmac_f32_e32 v186, v131, v131
	v_fmac_f32_e32 v190, 0.5, v141
	v_and_b32_e32 v141, 0xffff0000, v138
	v_fmac_f32_e32 v186, v140, v140
	v_cvt_pk_bf16_f32 v139, v189, v190
	v_fmac_f32_e32 v186, v141, v141
	v_lshlrev_b32_e32 v142, 16, v139
	v_and_b32_e32 v143, 0xffff0000, v139
	v_fmac_f32_e32 v186, v142, v142
	v_fmac_f32_e32 v186, v143, v143
	ds_bpermute_b32 v128, v237, v186
	v_lshl_add_u64 v[130:131], s[28:29], 0, v[176:177]
	v_lshl_add_u64 v[130:131], v[168:169], 1, v[130:131]
	global_store_dwordx4 v[130:131], v[132:135], off
	global_store_dwordx4 v[130:131], v[136:139], off offset:256
	s_waitcnt lgkmcnt(0)
	v_add_f32_e32 v128, v186, v128
	ds_bpermute_b32 v129, v238, v128
	s_waitcnt lgkmcnt(0)
	v_add_f32_e32 v251, v128, v129
;     __device__ __forceinline__ void operator()(const f32x4 (&acc)[2][2][4][2], const Unit& u, int wr, int wc, int fr, int fq) const {
;     ...
;                 u32x4 xin[2][2];
; #pragma unroll
;                 for (int mm = 0; mm < 2; ++mm)
; #pragma unroll
;                     for (int bj = 0; bj < 2; ++bj) xin[mm][bj] = *(const u32x4*)(X + (size_t)(row0 + ai * HALF + (mp * 2 + mm) * 16) * DM + col0 + bj * HALF);
;                 f32x4 pv[2][2][2];
; #pragma unroll
;                 for (int mm = 0; mm < 2; ++mm)
; #pragma unroll
;                     for (int bj = 0; bj < 2; ++bj)
; #pragma unroll
;                         for (int n = 0; n < 2; ++n) pv[mm][bj][n] = (f32x4){0.f, 0.f, 0.f, 0.f};
;                 if (src) {
;                     u32x4 pc[2][2];
;     ...
;                     asm volatile("global_load_dwordx4 %0, %4, off sc1\n\tglobal_load_dwordx4 %1, %5, off sc1\n\tglobal_load_dwordx4 %2, %6, off sc1\n\tglobal_load_dwordx4 %3, %7, off sc1\n\ts_waitcnt vmcnt(0)"
;                                  : "=&v"(pc[0][0]), "=&v"(pc[0][1]), "=&v"(pc[1][0]), "=&v"(pc[1][1])
;                                  : "v"(src + CI(0, 0)), "v"(src + CI(0, 1)), "v"(src + CI(1, 0)), "v"(src + CI(1, 1))
;                                  : "memory");
;     ...
; #pragma unroll
;                     for (int mm = 0; mm < 2; ++mm)
; #pragma unroll
;                         for (int bj = 0; bj < 2; ++bj) { float f[8]; unpack8(pc[mm][bj], f); pv[mm][bj][0] = (f32x4){f[0], f[1], f[2], f[3]}; pv[mm][bj][1] = (f32x4){f[4], f[5], f[6], f[7]}; }
;                 }
; #pragma unroll
;                 for (int mm = 0; mm < 2; ++mm) {
;                     const int m = mp * 2 + mm;
;                     const int row = row0 + ai * HALF + m * 16;
;                     float s = 0.f;
; #pragma unroll
;                     for (int bj = 0; bj < 2; ++bj) {
;                         u32x4* px = (u32x4*)(X + (size_t)row * DM + col0 + bj * HALF);
;                         float xo[8]; unpack8(xin[mm][bj], xo);
;                         const f32x4 a0 = acc[ai][bj][m][0] + pv[mm][bj][0], a1 = acc[ai][bj][m][1] + pv[mm][bj][1];
;                         u32x4 w;
;                         w.x = cvt_pk(xo[0] + scale * a0[0], xo[1] + scale * a0[1]); w.y = cvt_pk(xo[2] + scale * a0[2], xo[3] + scale * a0[3]);
.LBB0_409:
	v_or_b32_e32 v128, 32, v166
	s_waitcnt lgkmcnt(0)
	v_ashrrev_i32_e32 v129, 31, v128
	v_lshlrev_b64 v[186:187], 11, v[128:129]
	v_lshl_add_u64 v[128:129], v[172:173], 0, v[186:187]
	global_load_dwordx4 v[140:143], v[128:129], off
	global_load_dwordx4 v[136:139], v[128:129], off offset:256
	v_or_b32_e32 v128, 48, v166
	v_ashrrev_i32_e32 v129, 31, v128
	v_lshlrev_b64 v[176:177], 11, v[128:129]
	v_lshl_add_u64 v[128:129], v[172:173], 0, v[176:177]
	global_load_dwordx4 v[132:135], v[128:129], off
	s_nop 0
	global_load_dwordx4 v[128:131], v[128:129], off offset:256
	v_mov_b32_e32 v178, 0
	v_mov_b32_e32 v179, 0
	v_mov_b32_e32 v180, 0
	v_mov_b32_e32 v181, 0
	v_mov_b32_e32 v182, 0
	v_mov_b32_e32 v183, 0
	v_mov_b32_e32 v184, 0
	v_mov_b32_e32 v185, 0
	v_mov_b32_e32 v188, 0
	v_mov_b32_e32 v189, 0
	v_mov_b32_e32 v190, 0
	v_mov_b32_e32 v191, 0
	v_mov_b32_e32 v192, 0
	v_mov_b32_e32 v193, 0
	v_mov_b32_e32 v194, 0
	v_mov_b32_e32 v195, 0
	v_mov_b32_e32 v196, 0
	v_mov_b32_e32 v197, 0
	v_mov_b32_e32 v198, 0
	v_mov_b32_e32 v199, 0
	v_mov_b32_e32 v200, 0
	v_mov_b32_e32 v201, 0
	v_mov_b32_e32 v202, 0
	v_mov_b32_e32 v203, 0
	v_mov_b32_e32 v204, 0
	v_mov_b32_e32 v205, 0
	v_mov_b32_e32 v206, 0
	v_mov_b32_e32 v207, 0
	v_mov_b32_e32 v208, 0
	v_mov_b32_e32 v209, 0
	v_mov_b32_e32 v210, 0
	v_mov_b32_e32 v211, 0
	s_and_saveexec_b64 s[12:13], vcc
	s_cbranch_execz .LBB0_411
	s_mov_b64 s[30:31], 0x800
	v_lshl_add_u64 v[192:193], v[170:171], 0, s[30:31]
	s_mov_b64 s[30:31], 0x1800
	v_lshl_add_u64 v[194:195], v[170:171], 0, s[30:31]
	s_mov_b64 s[30:31], 0xc00
	v_lshl_add_u64 v[196:197], v[170:171], 0, s[30:31]
	s_mov_b64 s[30:31], 0x1c00
	v_lshl_add_u64 v[198:199], v[170:171], 0, s[30:31]
	global_load_dwordx4 v[178:181], v[192:193], off sc1
	global_load_dwordx4 v[182:185], v[194:195], off sc1
	global_load_dwordx4 v[188:191], v[196:197], off sc1
	global_load_dwordx4 v[244:247], v[198:199], off sc1
	s_waitcnt vmcnt(0)
	s_nop 0
	v_lshlrev_b32_e32 v208, 16, v178
	v_and_b32_e32 v209, 0xffff0000, v178
	v_lshlrev_b32_e32 v210, 16, v179
	v_and_b32_e32 v211, 0xffff0000, v179
	v_lshlrev_b32_e32 v204, 16, v180
	v_and_b32_e32 v205, 0xffff0000, v180
	v_lshlrev_b32_e32 v206, 16, v181
	v_and_b32_e32 v207, 0xffff0000, v181
	v_lshlrev_b32_e32 v200, 16, v182
	v_and_b32_e32 v201, 0xffff0000, v182
	v_lshlrev_b32_e32 v202, 16, v183
	v_and_b32_e32 v203, 0xffff0000, v183
	v_lshlrev_b32_e32 v196, 16, v184
	v_and_b32_e32 v197, 0xffff0000, v184
	v_lshlrev_b32_e32 v198, 16, v185
	v_and_b32_e32 v199, 0xffff0000, v185
	v_lshlrev_b32_e32 v192, 16, v188
	v_and_b32_e32 v193, 0xffff0000, v188
	v_lshlrev_b32_e32 v194, 16, v189
	v_and_b32_e32 v195, 0xffff0000, v189
	v_lshlrev_b32_e32 v188, 16, v190
	v_and_b32_e32 v189, 0xffff0000, v190
	v_lshlrev_b32_e32 v190, 16, v191
	v_and_b32_e32 v191, 0xffff0000, v191
	v_lshlrev_b32_e32 v182, 16, v244
	v_and_b32_e32 v183, 0xffff0000, v244
	v_lshlrev_b32_e32 v184, 16, v245
	v_and_b32_e32 v185, 0xffff0000, v245
	v_lshlrev_b32_e32 v178, 16, v246
	v_and_b32_e32 v179, 0xffff0000, v246
	v_lshlrev_b32_e32 v180, 16, v247
	v_and_b32_e32 v181, 0xffff0000, v247
.LBB0_411:
	s_or_b64 exec, exec, s[12:13]
	s_waitcnt vmcnt(3)
	s_and_saveexec_b64 s[12:13], s[8:9]
	v_lshl_add_u64 v[252:253], v[166:167], 2, s[6:7]
	global_atomic_add_f32 v[252:253], v250, off
	global_atomic_add_f32 v[252:253], v251, off offset:64
	s_or_b64 exec, exec, s[12:13]
	v_lshlrev_b32_e32 v214, 16, v140
	v_and_b32_e32 v215, 0xffff0000, v140
	v_lshlrev_b32_e32 v244, 16, v141
	v_and_b32_e32 v245, 0xffff0000, v141
	v_and_b32_e32 v247, 0xffff0000, v142
	v_pk_add_f32 v[140:141], v[108:109], v[208:209]
	v_pk_add_f32 v[204:205], v[104:105], v[204:205]
	v_lshlrev_b32_e32 v246, 16, v142
	v_fmac_f32_e32 v214, 0.5, v140
	v_fmac_f32_e32 v215, 0.5, v141
	v_cvt_pk_bf16_f32 v140, v214, v215
	v_fmac_f32_e32 v247, 0.5, v205
	v_and_b32_e32 v205, 0xffff0000, v140
	v_lshlrev_b32_e32 v248, 16, v143
	v_and_b32_e32 v249, 0xffff0000, v143
	v_pk_add_f32 v[142:143], v[110:111], v[210:211]
	v_pk_add_f32 v[206:207], v[106:107], v[206:207]
	v_fmac_f32_e32 v246, 0.5, v204
	v_lshlrev_b32_e32 v204, 16, v140
	v_mul_f32_e32 v205, v205, v205
	v_fmac_f32_e32 v244, 0.5, v142
	v_fmac_f32_e32 v245, 0.5, v143
	v_cvt_pk_bf16_f32 v141, v244, v245
	v_fmac_f32_e32 v248, 0.5, v206
	v_lshlrev_b32_e32 v206, 16, v141
	v_fmac_f32_e32 v205, v204, v204
	v_fmac_f32_e32 v249, 0.5, v207
	v_and_b32_e32 v207, 0xffff0000, v141
	v_fmac_f32_e32 v205, v206, v206
	v_cvt_pk_bf16_f32 v142, v246, v247
	v_fmac_f32_e32 v205, v207, v207
	v_lshlrev_b32_e32 v208, 16, v142
	v_and_b32_e32 v209, 0xffff0000, v142
	v_fmac_f32_e32 v205, v208, v208
	v_cvt_pk_bf16_f32 v143, v248, v249
	v_fmac_f32_e32 v205, v209, v209
	v_lshlrev_b32_e32 v210, 16, v143
	v_and_b32_e32 v211, 0xffff0000, v143
	v_fmac_f32_e32 v205, v210, v210
	v_fmac_f32_e32 v205, v211, v211
	s_waitcnt vmcnt(4)
	v_lshlrev_b32_e32 v204, 16, v136
	v_and_b32_e32 v206, 0xffff0000, v136
	v_lshlrev_b32_e32 v207, 16, v137
	v_and_b32_e32 v208, 0xffff0000, v137
	v_lshlrev_b32_e32 v209, 16, v138
	v_and_b32_e32 v210, 0xffff0000, v138
	v_lshlrev_b32_e32 v211, 16, v139
	v_and_b32_e32 v214, 0xffff0000, v139
	v_pk_add_f32 v[136:137], v[78:79], v[202:203]
	v_pk_add_f32 v[138:139], v[76:77], v[200:201]
	v_pk_add_f32 v[200:201], v[74:75], v[198:199]
	v_pk_add_f32 v[198:199], v[72:73], v[196:197]
	v_fmac_f32_e32 v204, 0.5, v138
	v_fmac_f32_e32 v206, 0.5, v139
	v_cvt_pk_bf16_f32 v196, v204, v206
	v_fmac_f32_e32 v207, 0.5, v136
	v_lshlrev_b32_e32 v136, 16, v196
	v_fmac_f32_e32 v208, 0.5, v137
	v_and_b32_e32 v137, 0xffff0000, v196
	v_fmac_f32_e32 v205, v136, v136
	v_cvt_pk_bf16_f32 v197, v207, v208
	v_fmac_f32_e32 v205, v137, v137
	v_lshlrev_b32_e32 v138, 16, v197
	v_and_b32_e32 v139, 0xffff0000, v197
	v_fmac_f32_e32 v205, v138, v138
	v_fmac_f32_e32 v209, 0.5, v198
	v_fmac_f32_e32 v210, 0.5, v199
	v_cvt_pk_bf16_f32 v198, v209, v210
	v_fmac_f32_e32 v211, 0.5, v200
	v_lshlrev_b32_e32 v200, 16, v198
	v_fmac_f32_e32 v205, v139, v139
	v_fmac_f32_e32 v214, 0.5, v201
	v_and_b32_e32 v201, 0xffff0000, v198
	v_fmac_f32_e32 v205, v200, v200
	v_cvt_pk_bf16_f32 v199, v211, v214
	v_fmac_f32_e32 v205, v201, v201
	v_lshlrev_b32_e32 v202, 16, v199
	v_and_b32_e32 v203, 0xffff0000, v199
	v_fmac_f32_e32 v205, v202, v202
	v_fmac_f32_e32 v205, v203, v203
	ds_bpermute_b32 v136, v237, v205
	v_lshl_add_u64 v[138:139], s[28:29], 0, v[186:187]
	v_lshl_add_u64 v[138:139], v[168:169], 1, v[138:139]
	global_store_dwordx4 v[138:139], v[140:143], off
	global_store_dwordx4 v[138:139], v[196:199], off offset:256
	s_waitcnt lgkmcnt(0)
	v_add_f32_e32 v136, v205, v136
	ds_bpermute_b32 v137, v238, v136
	s_waitcnt lgkmcnt(0)
	v_add_f32_e32 v250, v136, v137
;     __device__ __forceinline__ void operator()(const f32x4 (&acc)[2][2][4][2], const Unit& u, int wr, int wc, int fr, int fq) const {
;     ...
;                 u32x4 xin[2][2];
; #pragma unroll
;                 for (int mm = 0; mm < 2; ++mm)
; #pragma unroll
;                     for (int bj = 0; bj < 2; ++bj) xin[mm][bj] = *(const u32x4*)(X + (size_t)(row0 + ai * HALF + (mp * 2 + mm) * 16) * DM + col0 + bj * HALF);
;                 f32x4 pv[2][2][2];
; #pragma unroll
;                 for (int mm = 0; mm < 2; ++mm)
; #pragma unroll
;                     for (int bj = 0; bj < 2; ++bj)
; #pragma unroll
;                         for (int n = 0; n < 2; ++n) pv[mm][bj][n] = (f32x4){0.f, 0.f, 0.f, 0.f};
;                 if (src) {
;                     u32x4 pc[2][2];
;     ...
;                     asm volatile("global_load_dwordx4 %0, %4, off sc1\n\tglobal_load_dwordx4 %1, %5, off sc1\n\tglobal_load_dwordx4 %2, %6, off sc1\n\tglobal_load_dwordx4 %3, %7, off sc1\n\ts_waitcnt vmcnt(0)"
;                                  : "=&v"(pc[0][0]), "=&v"(pc[0][1]), "=&v"(pc[1][0]), "=&v"(pc[1][1])
;                                  : "v"(src + CI(0, 0)), "v"(src + CI(0, 1)), "v"(src + CI(1, 0)), "v"(src + CI(1, 1))
;                                  : "memory");
;     ...
; #pragma unroll
;                     for (int mm = 0; mm < 2; ++mm)
; #pragma unroll
;                         for (int bj = 0; bj < 2; ++bj) { float f[8]; unpack8(pc[mm][bj], f); pv[mm][bj][0] = (f32x4){f[0], f[1], f[2], f[3]}; pv[mm][bj][1] = (f32x4){f[4], f[5], f[6], f[7]}; }
;                 }
; #pragma unroll
;                 for (int mm = 0; mm < 2; ++mm) {
;                     const int m = mp * 2 + mm;
;                     const int row = row0 + ai * HALF + m * 16;
;                     float s = 0.f;
; #pragma unroll
;                     for (int bj = 0; bj < 2; ++bj) {
;                         u32x4* px = (u32x4*)(X + (size_t)row * DM + col0 + bj * HALF);
;                         float xo[8]; unpack8(xin[mm][bj], xo);
;                         const f32x4 a0 = acc[ai][bj][m][0] + pv[mm][bj][0], a1 = acc[ai][bj][m][1] + pv[mm][bj][1];
;                         u32x4 w;
;                         w.x = cvt_pk(xo[0] + scale * a0[0], xo[1] + scale * a0[1]); w.y = cvt_pk(xo[2] + scale * a0[2], xo[3] + scale * a0[3]);
.LBB0_413:
	s_waitcnt vmcnt(5)
	v_lshlrev_b32_e32 v140, 16, v132
	v_and_b32_e32 v141, 0xffff0000, v132
	v_lshlrev_b32_e32 v142, 16, v133
	v_and_b32_e32 v143, 0xffff0000, v133
	v_lshlrev_b32_e32 v186, 16, v134
	v_and_b32_e32 v197, 0xffff0000, v135
	v_pk_add_f32 v[132:133], v[100:101], v[192:193]
	s_waitcnt lgkmcnt(0)
	v_pk_add_f32 v[136:137], v[98:99], v[190:191]
	v_pk_add_f32 v[138:139], v[96:97], v[188:189]
	v_and_b32_e32 v187, 0xffff0000, v134
	v_lshlrev_b32_e32 v196, 16, v135
	v_pk_add_f32 v[134:135], v[102:103], v[194:195]
	v_fmac_f32_e32 v140, 0.5, v132
	v_fmac_f32_e32 v141, 0.5, v133
	v_cvt_pk_bf16_f32 v132, v140, v141
	v_fmac_f32_e32 v186, 0.5, v138
	v_fmac_f32_e32 v197, 0.5, v137
	v_and_b32_e32 v137, 0xffff0000, v132
	v_fmac_f32_e32 v142, 0.5, v134
	v_fmac_f32_e32 v187, 0.5, v139
	v_cvt_pk_bf16_f32 v134, v186, v187
	v_fmac_f32_e32 v196, 0.5, v136
	v_lshlrev_b32_e32 v136, 16, v132
	v_mul_f32_e32 v186, v137, v137
	v_fmac_f32_e32 v143, 0.5, v135
	v_cvt_pk_bf16_f32 v133, v142, v143
	v_fmac_f32_e32 v186, v136, v136
	v_lshlrev_b32_e32 v138, 16, v133
	v_and_b32_e32 v139, 0xffff0000, v133
	v_fmac_f32_e32 v186, v138, v138
	v_lshlrev_b32_e32 v140, 16, v134
	v_fmac_f32_e32 v186, v139, v139
	v_and_b32_e32 v141, 0xffff0000, v134
	v_fmac_f32_e32 v186, v140, v140
	v_cvt_pk_bf16_f32 v135, v196, v197
	v_fmac_f32_e32 v186, v141, v141
	v_lshlrev_b32_e32 v142, 16, v135
	v_and_b32_e32 v143, 0xffff0000, v135
	v_fmac_f32_e32 v186, v142, v142
	s_waitcnt vmcnt(4)
	v_lshlrev_b32_e32 v136, 16, v128
	v_lshlrev_b32_e32 v187, 16, v130
	v_and_b32_e32 v188, 0xffff0000, v130
	v_lshlrev_b32_e32 v189, 16, v131
	v_and_b32_e32 v190, 0xffff0000, v131
	v_pk_add_f32 v[130:131], v[68:69], v[182:183]
	v_fmac_f32_e32 v186, v143, v143
	v_and_b32_e32 v137, 0xffff0000, v128
	v_lshlrev_b32_e32 v142, 16, v129
	v_and_b32_e32 v143, 0xffff0000, v129
	v_pk_add_f32 v[128:129], v[70:71], v[184:185]
	v_fmac_f32_e32 v136, 0.5, v130
	v_fmac_f32_e32 v137, 0.5, v131
	v_cvt_pk_bf16_f32 v136, v136, v137
	v_fmac_f32_e32 v142, 0.5, v128
	v_lshlrev_b32_e32 v128, 16, v136
	v_fmac_f32_e32 v143, 0.5, v129
	v_and_b32_e32 v129, 0xffff0000, v136
	v_fmac_f32_e32 v186, v128, v128
	v_cvt_pk_bf16_f32 v137, v142, v143
	v_fmac_f32_e32 v186, v129, v129
	v_lshlrev_b32_e32 v130, 16, v137
	v_pk_add_f32 v[140:141], v[66:67], v[180:181]
	v_pk_add_f32 v[138:139], v[64:65], v[178:179]
	v_and_b32_e32 v131, 0xffff0000, v137
	v_fmac_f32_e32 v186, v130, v130
	v_fmac_f32_e32 v187, 0.5, v138
	v_fmac_f32_e32 v188, 0.5, v139
	v_cvt_pk_bf16_f32 v138, v187, v188
	v_fmac_f32_e32 v189, 0.5, v140
	v_lshlrev_b32_e32 v140, 16, v138
	v_fmac_f32_e32 v186, v131, v131
	v_fmac_f32_e32 v190, 0.5, v141
	v_and_b32_e32 v141, 0xffff0000, v138
	v_fmac_f32_e32 v186, v140, v140
	v_cvt_pk_bf16_f32 v139, v189, v190
	v_fmac_f32_e32 v186, v141, v141
	v_lshlrev_b32_e32 v142, 16, v139
	v_and_b32_e32 v143, 0xffff0000, v139
	v_fmac_f32_e32 v186, v142, v142
	v_fmac_f32_e32 v186, v143, v143
	ds_bpermute_b32 v128, v237, v186
	v_lshl_add_u64 v[130:131], s[28:29], 0, v[176:177]
	v_lshl_add_u64 v[130:131], v[168:169], 1, v[130:131]
	global_store_dwordx4 v[130:131], v[132:135], off
	global_store_dwordx4 v[130:131], v[136:139], off offset:256
	s_waitcnt lgkmcnt(0)
	v_add_f32_e32 v128, v186, v128
	ds_bpermute_b32 v129, v238, v128
	s_waitcnt lgkmcnt(0)
	v_add_f32_e32 v251, v128, v129
.LBB0_415:
	s_mov_b64 s[12:13], 0x40000
	v_lshl_add_u64 v[186:187], v[174:175], 0, s[12:13]
	s_mov_b64 s[12:13], 0x48000
	s_waitcnt lgkmcnt(0)
	v_lshl_add_u64 v[128:129], v[172:173], 0, v[186:187]
	v_lshl_add_u64 v[176:177], v[174:175], 0, s[12:13]
	global_load_dwordx4 v[140:143], v[128:129], off
	global_load_dwordx4 v[136:139], v[128:129], off offset:256
	v_lshl_add_u64 v[128:129], v[172:173], 0, v[176:177]
	global_load_dwordx4 v[132:135], v[128:129], off
	s_nop 0
	global_load_dwordx4 v[128:131], v[128:129], off offset:256
	v_mov_b32_e32 v178, 0
	v_mov_b32_e32 v179, 0
	v_mov_b32_e32 v180, 0
	v_mov_b32_e32 v181, 0
	v_mov_b32_e32 v182, 0
	v_mov_b32_e32 v183, 0
	v_mov_b32_e32 v184, 0
	v_mov_b32_e32 v185, 0
	v_mov_b32_e32 v188, 0
	v_mov_b32_e32 v189, 0
	v_mov_b32_e32 v190, 0
	v_mov_b32_e32 v191, 0
	v_mov_b32_e32 v192, 0
	v_mov_b32_e32 v193, 0
	v_mov_b32_e32 v194, 0
	v_mov_b32_e32 v195, 0
	v_mov_b32_e32 v196, 0
	v_mov_b32_e32 v197, 0
	v_mov_b32_e32 v198, 0
	v_mov_b32_e32 v199, 0
	v_mov_b32_e32 v200, 0
	v_mov_b32_e32 v201, 0
	v_mov_b32_e32 v202, 0
	v_mov_b32_e32 v203, 0
	v_mov_b32_e32 v204, 0
	v_mov_b32_e32 v205, 0
	v_mov_b32_e32 v206, 0
	v_mov_b32_e32 v207, 0
	v_mov_b32_e32 v208, 0
	v_mov_b32_e32 v209, 0
	v_mov_b32_e32 v210, 0
	v_mov_b32_e32 v211, 0
	s_and_saveexec_b64 s[12:13], vcc
	s_cbranch_execz .LBB0_417
	s_mov_b64 s[30:31], 0x2000
	v_lshl_add_u64 v[192:193], v[170:171], 0, s[30:31]
	s_mov_b64 s[30:31], 0x3000
	v_lshl_add_u64 v[194:195], v[170:171], 0, s[30:31]
	s_mov_b64 s[30:31], 0x2400
	v_lshl_add_u64 v[196:197], v[170:171], 0, s[30:31]
	s_mov_b64 s[30:31], 0x3400
	v_lshl_add_u64 v[198:199], v[170:171], 0, s[30:31]
	global_load_dwordx4 v[178:181], v[192:193], off sc1
	global_load_dwordx4 v[182:185], v[194:195], off sc1
	global_load_dwordx4 v[188:191], v[196:197], off sc1
	global_load_dwordx4 v[244:247], v[198:199], off sc1
	s_waitcnt vmcnt(0)
	s_nop 0
	v_lshlrev_b32_e32 v208, 16, v178
	v_and_b32_e32 v209, 0xffff0000, v178
	v_lshlrev_b32_e32 v210, 16, v179
	v_and_b32_e32 v211, 0xffff0000, v179
	v_lshlrev_b32_e32 v204, 16, v180
	v_and_b32_e32 v205, 0xffff0000, v180
	v_lshlrev_b32_e32 v206, 16, v181
	v_and_b32_e32 v207, 0xffff0000, v181
	v_lshlrev_b32_e32 v200, 16, v182
	v_and_b32_e32 v201, 0xffff0000, v182
	v_lshlrev_b32_e32 v202, 16, v183
	v_and_b32_e32 v203, 0xffff0000, v183
	v_lshlrev_b32_e32 v196, 16, v184
	v_and_b32_e32 v197, 0xffff0000, v184
	v_lshlrev_b32_e32 v198, 16, v185
	v_and_b32_e32 v199, 0xffff0000, v185
	v_lshlrev_b32_e32 v192, 16, v188
	v_and_b32_e32 v193, 0xffff0000, v188
	v_lshlrev_b32_e32 v194, 16, v189
	v_and_b32_e32 v195, 0xffff0000, v189
	v_lshlrev_b32_e32 v188, 16, v190
	v_and_b32_e32 v189, 0xffff0000, v190
	v_lshlrev_b32_e32 v190, 16, v191
	v_and_b32_e32 v191, 0xffff0000, v191
	v_lshlrev_b32_e32 v182, 16, v244
	v_and_b32_e32 v183, 0xffff0000, v244
	v_lshlrev_b32_e32 v184, 16, v245
	v_and_b32_e32 v185, 0xffff0000, v245
	v_lshlrev_b32_e32 v178, 16, v246
	v_and_b32_e32 v179, 0xffff0000, v246
	v_lshlrev_b32_e32 v180, 16, v247
	v_and_b32_e32 v181, 0xffff0000, v247
;     __device__ __forceinline__ void operator()(const f32x4 (&acc)[2][2][4][2], const Unit& u, int wr, int wc, int fr, int fq) const {
;     ...
;                 u32x4 xin[2][2];
; #pragma unroll
;                 for (int mm = 0; mm < 2; ++mm)
; #pragma unroll
;                     for (int bj = 0; bj < 2; ++bj) xin[mm][bj] = *(const u32x4*)(X + (size_t)(row0 + ai * HALF + (mp * 2 + mm) * 16) * DM + col0 + bj * HALF);
;                 f32x4 pv[2][2][2];
; #pragma unroll
;                 for (int mm = 0; mm < 2; ++mm)
; #pragma unroll
;                     for (int bj = 0; bj < 2; ++bj)
; #pragma unroll
;                         for (int n = 0; n < 2; ++n) pv[mm][bj][n] = (f32x4){0.f, 0.f, 0.f, 0.f};
;                 if (src) {
;                     u32x4 pc[2][2];
;     ...
;                     asm volatile("global_load_dwordx4 %0, %4, off sc1\n\tglobal_load_dwordx4 %1, %5, off sc1\n\tglobal_load_dwordx4 %2, %6, off sc1\n\tglobal_load_dwordx4 %3, %7, off sc1\n\ts_waitcnt vmcnt(0)"
;                                  : "=&v"(pc[0][0]), "=&v"(pc[0][1]), "=&v"(pc[1][0]), "=&v"(pc[1][1])
;                                  : "v"(src + CI(0, 0)), "v"(src + CI(0, 1)), "v"(src + CI(1, 0)), "v"(src + CI(1, 1))
;                                  : "memory");
;     ...
; #pragma unroll
;                     for (int mm = 0; mm < 2; ++mm)
; #pragma unroll
;                         for (int bj = 0; bj < 2; ++bj) { float f[8]; unpack8(pc[mm][bj], f); pv[mm][bj][0] = (f32x4){f[0], f[1], f[2], f[3]}; pv[mm][bj][1] = (f32x4){f[4], f[5], f[6], f[7]}; }
;                 }
; #pragma unroll
;                 for (int mm = 0; mm < 2; ++mm) {
;                     const int m = mp * 2 + mm;
;                     const int row = row0 + ai * HALF + m * 16;
;                     float s = 0.f;
; #pragma unroll
;                     for (int bj = 0; bj < 2; ++bj) {
;                         u32x4* px = (u32x4*)(X + (size_t)row * DM + col0 + bj * HALF);
;                         float xo[8]; unpack8(xin[mm][bj], xo);
;                         const f32x4 a0 = acc[ai][bj][m][0] + pv[mm][bj][0], a1 = acc[ai][bj][m][1] + pv[mm][bj][1];
;                         u32x4 w;
;                         w.x = cvt_pk(xo[0] + scale * a0[0], xo[1] + scale * a0[1]); w.y = cvt_pk(xo[2] + scale * a0[2], xo[3] + scale * a0[3]);
.LBB0_417:
	s_or_b64 exec, exec, s[12:13]
	s_waitcnt vmcnt(3)
	s_and_saveexec_b64 s[12:13], s[8:9]
	v_lshl_add_u64 v[252:253], v[166:167], 2, s[6:7]
	global_atomic_add_f32 v[252:253], v250, off offset:128
	global_atomic_add_f32 v[252:253], v251, off offset:192
	s_or_b64 exec, exec, s[12:13]
	v_lshlrev_b32_e32 v214, 16, v140
	v_and_b32_e32 v215, 0xffff0000, v140
	v_lshlrev_b32_e32 v244, 16, v141
	v_and_b32_e32 v245, 0xffff0000, v141
	v_and_b32_e32 v247, 0xffff0000, v142
	v_pk_add_f32 v[140:141], v[60:61], v[208:209]
	v_pk_add_f32 v[204:205], v[56:57], v[204:205]
	v_lshlrev_b32_e32 v246, 16, v142
	v_fmac_f32_e32 v214, 0.5, v140
	v_fmac_f32_e32 v215, 0.5, v141
	v_cvt_pk_bf16_f32 v140, v214, v215
	v_fmac_f32_e32 v247, 0.5, v205
	v_and_b32_e32 v205, 0xffff0000, v140
	v_lshlrev_b32_e32 v248, 16, v143
	v_and_b32_e32 v249, 0xffff0000, v143
	v_pk_add_f32 v[142:143], v[62:63], v[210:211]
	v_pk_add_f32 v[206:207], v[58:59], v[206:207]
	v_fmac_f32_e32 v246, 0.5, v204
	v_lshlrev_b32_e32 v204, 16, v140
	v_mul_f32_e32 v205, v205, v205
	v_fmac_f32_e32 v244, 0.5, v142
	v_fmac_f32_e32 v245, 0.5, v143
	v_cvt_pk_bf16_f32 v141, v244, v245
	v_fmac_f32_e32 v248, 0.5, v206
	v_lshlrev_b32_e32 v206, 16, v141
	v_fmac_f32_e32 v205, v204, v204
	v_fmac_f32_e32 v249, 0.5, v207
	v_and_b32_e32 v207, 0xffff0000, v141
	v_fmac_f32_e32 v205, v206, v206
	v_cvt_pk_bf16_f32 v142, v246, v247
	v_fmac_f32_e32 v205, v207, v207
	v_lshlrev_b32_e32 v208, 16, v142
	v_and_b32_e32 v209, 0xffff0000, v142
	v_fmac_f32_e32 v205, v208, v208
	v_cvt_pk_bf16_f32 v143, v248, v249
	v_fmac_f32_e32 v205, v209, v209
	v_lshlrev_b32_e32 v210, 16, v143
	v_and_b32_e32 v211, 0xffff0000, v143
	v_fmac_f32_e32 v205, v210, v210
	v_fmac_f32_e32 v205, v211, v211
	s_waitcnt vmcnt(4)
	v_lshlrev_b32_e32 v204, 16, v136
	v_and_b32_e32 v206, 0xffff0000, v136
	v_lshlrev_b32_e32 v207, 16, v137
	v_and_b32_e32 v208, 0xffff0000, v137
	v_lshlrev_b32_e32 v209, 16, v138
	v_and_b32_e32 v210, 0xffff0000, v138
	v_lshlrev_b32_e32 v211, 16, v139
	v_and_b32_e32 v214, 0xffff0000, v139
	v_pk_add_f32 v[136:137], v[30:31], v[202:203]
	v_pk_add_f32 v[138:139], v[28:29], v[200:201]
	v_pk_add_f32 v[200:201], v[26:27], v[198:199]
	v_pk_add_f32 v[198:199], v[24:25], v[196:197]
	v_fmac_f32_e32 v204, 0.5, v138
	v_fmac_f32_e32 v206, 0.5, v139
	v_cvt_pk_bf16_f32 v196, v204, v206
	v_fmac_f32_e32 v207, 0.5, v136
	v_lshlrev_b32_e32 v136, 16, v196
	v_fmac_f32_e32 v208, 0.5, v137
	v_and_b32_e32 v137, 0xffff0000, v196
	v_fmac_f32_e32 v205, v136, v136
	v_cvt_pk_bf16_f32 v197, v207, v208
	v_fmac_f32_e32 v205, v137, v137
	v_lshlrev_b32_e32 v138, 16, v197
	v_and_b32_e32 v139, 0xffff0000, v197
	v_fmac_f32_e32 v205, v138, v138
	v_fmac_f32_e32 v209, 0.5, v198
	v_fmac_f32_e32 v210, 0.5, v199
	v_cvt_pk_bf16_f32 v198, v209, v210
	v_fmac_f32_e32 v211, 0.5, v200
	v_lshlrev_b32_e32 v200, 16, v198
	v_fmac_f32_e32 v205, v139, v139
	v_fmac_f32_e32 v214, 0.5, v201
	v_and_b32_e32 v201, 0xffff0000, v198
	v_fmac_f32_e32 v205, v200, v200
	v_cvt_pk_bf16_f32 v199, v211, v214
	v_fmac_f32_e32 v205, v201, v201
	v_lshlrev_b32_e32 v202, 16, v199
	v_and_b32_e32 v203, 0xffff0000, v199
	v_fmac_f32_e32 v205, v202, v202
	v_fmac_f32_e32 v205, v203, v203
	ds_bpermute_b32 v136, v237, v205
	v_lshl_add_u64 v[138:139], s[28:29], 0, v[186:187]
	v_lshl_add_u64 v[138:139], v[168:169], 1, v[138:139]
	global_store_dwordx4 v[138:139], v[140:143], off
	global_store_dwordx4 v[138:139], v[196:199], off offset:256
	s_waitcnt lgkmcnt(0)
	v_add_f32_e32 v136, v205, v136
	ds_bpermute_b32 v137, v238, v136
	s_waitcnt lgkmcnt(0)
	v_add_f32_e32 v250, v136, v137
.LBB0_419:
	s_waitcnt vmcnt(5)
	v_lshlrev_b32_e32 v140, 16, v132
	v_and_b32_e32 v141, 0xffff0000, v132
	v_lshlrev_b32_e32 v142, 16, v133
	v_and_b32_e32 v143, 0xffff0000, v133
	v_lshlrev_b32_e32 v186, 16, v134
	v_and_b32_e32 v197, 0xffff0000, v135
	v_pk_add_f32 v[132:133], v[52:53], v[192:193]
	s_waitcnt lgkmcnt(0)
	v_pk_add_f32 v[136:137], v[50:51], v[190:191]
	v_pk_add_f32 v[138:139], v[48:49], v[188:189]
	v_and_b32_e32 v187, 0xffff0000, v134
	v_lshlrev_b32_e32 v196, 16, v135
	v_pk_add_f32 v[134:135], v[54:55], v[194:195]
	v_fmac_f32_e32 v140, 0.5, v132
	v_fmac_f32_e32 v141, 0.5, v133
	v_cvt_pk_bf16_f32 v132, v140, v141
	v_fmac_f32_e32 v186, 0.5, v138
	v_fmac_f32_e32 v197, 0.5, v137
	v_and_b32_e32 v137, 0xffff0000, v132
	v_fmac_f32_e32 v142, 0.5, v134
	v_fmac_f32_e32 v187, 0.5, v139
	v_cvt_pk_bf16_f32 v134, v186, v187
	v_fmac_f32_e32 v196, 0.5, v136
	v_lshlrev_b32_e32 v136, 16, v132
	v_mul_f32_e32 v186, v137, v137
	v_fmac_f32_e32 v143, 0.5, v135
	v_cvt_pk_bf16_f32 v133, v142, v143
	v_fmac_f32_e32 v186, v136, v136
	v_lshlrev_b32_e32 v138, 16, v133
	v_and_b32_e32 v139, 0xffff0000, v133
	v_fmac_f32_e32 v186, v138, v138
	v_lshlrev_b32_e32 v140, 16, v134
	v_fmac_f32_e32 v186, v139, v139
	v_and_b32_e32 v141, 0xffff0000, v134
	v_fmac_f32_e32 v186, v140, v140
	v_cvt_pk_bf16_f32 v135, v196, v197
	v_fmac_f32_e32 v186, v141, v141
	v_lshlrev_b32_e32 v142, 16, v135
	v_and_b32_e32 v143, 0xffff0000, v135
	v_fmac_f32_e32 v186, v142, v142
	s_waitcnt vmcnt(4)
	v_lshlrev_b32_e32 v136, 16, v128
	v_lshlrev_b32_e32 v187, 16, v130
	v_and_b32_e32 v188, 0xffff0000, v130
	v_lshlrev_b32_e32 v189, 16, v131
	v_and_b32_e32 v190, 0xffff0000, v131
	v_pk_add_f32 v[130:131], v[20:21], v[182:183]
	v_fmac_f32_e32 v186, v143, v143
	v_and_b32_e32 v137, 0xffff0000, v128
	v_lshlrev_b32_e32 v142, 16, v129
	v_and_b32_e32 v143, 0xffff0000, v129
	v_pk_add_f32 v[128:129], v[22:23], v[184:185]
	v_fmac_f32_e32 v136, 0.5, v130
	v_fmac_f32_e32 v137, 0.5, v131
	v_cvt_pk_bf16_f32 v136, v136, v137
	v_fmac_f32_e32 v142, 0.5, v128
	v_lshlrev_b32_e32 v128, 16, v136
	v_fmac_f32_e32 v143, 0.5, v129
	v_and_b32_e32 v129, 0xffff0000, v136
	v_fmac_f32_e32 v186, v128, v128
	v_cvt_pk_bf16_f32 v137, v142, v143
	v_fmac_f32_e32 v186, v129, v129
	v_lshlrev_b32_e32 v130, 16, v137
	v_pk_add_f32 v[140:141], v[18:19], v[180:181]
	v_pk_add_f32 v[138:139], v[16:17], v[178:179]
	v_and_b32_e32 v131, 0xffff0000, v137
	v_fmac_f32_e32 v186, v130, v130
	v_fmac_f32_e32 v187, 0.5, v138
	v_fmac_f32_e32 v188, 0.5, v139
	v_cvt_pk_bf16_f32 v138, v187, v188
	v_fmac_f32_e32 v189, 0.5, v140
	v_lshlrev_b32_e32 v140, 16, v138
	v_fmac_f32_e32 v186, v131, v131
	v_fmac_f32_e32 v190, 0.5, v141
	v_and_b32_e32 v141, 0xffff0000, v138
	v_fmac_f32_e32 v186, v140, v140
	v_cvt_pk_bf16_f32 v139, v189, v190
	v_fmac_f32_e32 v186, v141, v141
	v_lshlrev_b32_e32 v142, 16, v139
	v_and_b32_e32 v143, 0xffff0000, v139
	v_fmac_f32_e32 v186, v142, v142
	v_fmac_f32_e32 v186, v143, v143
	ds_bpermute_b32 v128, v237, v186
	v_lshl_add_u64 v[130:131], s[28:29], 0, v[176:177]
	v_lshl_add_u64 v[130:131], v[168:169], 1, v[130:131]
	global_store_dwordx4 v[130:131], v[132:135], off
	global_store_dwordx4 v[130:131], v[136:139], off offset:256
	s_waitcnt lgkmcnt(0)
	v_add_f32_e32 v128, v186, v128
	ds_bpermute_b32 v129, v238, v128
	s_waitcnt lgkmcnt(0)
	v_add_f32_e32 v251, v128, v129
;     __device__ __forceinline__ void operator()(const f32x4 (&acc)[2][2][4][2], const Unit& u, int wr, int wc, int fr, int fq) const {
;     ...
;                 u32x4 xin[2][2];
; #pragma unroll
;                 for (int mm = 0; mm < 2; ++mm)
; #pragma unroll
;                     for (int bj = 0; bj < 2; ++bj) xin[mm][bj] = *(const u32x4*)(X + (size_t)(row0 + ai * HALF + (mp * 2 + mm) * 16) * DM + col0 + bj * HALF);
;                 f32x4 pv[2][2][2];
; #pragma unroll
;                 for (int mm = 0; mm < 2; ++mm)
; #pragma unroll
;                     for (int bj = 0; bj < 2; ++bj)
; #pragma unroll
;                         for (int n = 0; n < 2; ++n) pv[mm][bj][n] = (f32x4){0.f, 0.f, 0.f, 0.f};
;                 if (src) {
;                     u32x4 pc[2][2];
;     ...
;                     asm volatile("global_load_dwordx4 %0, %4, off sc1\n\tglobal_load_dwordx4 %1, %5, off sc1\n\tglobal_load_dwordx4 %2, %6, off sc1\n\tglobal_load_dwordx4 %3, %7, off sc1\n\ts_waitcnt vmcnt(0)"
;                                  : "=&v"(pc[0][0]), "=&v"(pc[0][1]), "=&v"(pc[1][0]), "=&v"(pc[1][1])
;                                  : "v"(src + CI(0, 0)), "v"(src + CI(0, 1)), "v"(src + CI(1, 0)), "v"(src + CI(1, 1))
;                                  : "memory");
;     ...
; #pragma unroll
;                     for (int mm = 0; mm < 2; ++mm)
; #pragma unroll
;                         for (int bj = 0; bj < 2; ++bj) { float f[8]; unpack8(pc[mm][bj], f); pv[mm][bj][0] = (f32x4){f[0], f[1], f[2], f[3]}; pv[mm][bj][1] = (f32x4){f[4], f[5], f[6], f[7]}; }
;                 }
; #pragma unroll
;                 for (int mm = 0; mm < 2; ++mm) {
;                     const int m = mp * 2 + mm;
;                     const int row = row0 + ai * HALF + m * 16;
;                     float s = 0.f;
; #pragma unroll
;                     for (int bj = 0; bj < 2; ++bj) {
;                         u32x4* px = (u32x4*)(X + (size_t)row * DM + col0 + bj * HALF);
;                         float xo[8]; unpack8(xin[mm][bj], xo);
;                         const f32x4 a0 = acc[ai][bj][m][0] + pv[mm][bj][0], a1 = acc[ai][bj][m][1] + pv[mm][bj][1];
;                         u32x4 w;
;                         w.x = cvt_pk(xo[0] + scale * a0[0], xo[1] + scale * a0[1]); w.y = cvt_pk(xo[2] + scale * a0[2], xo[3] + scale * a0[3]);
.LBB0_421:
	s_mov_b64 s[12:13], 0x50000
	v_lshl_add_u64 v[182:183], v[174:175], 0, s[12:13]
	s_mov_b64 s[12:13], 0x58000
	s_waitcnt lgkmcnt(0)
	v_lshl_add_u64 v[128:129], v[172:173], 0, v[182:183]
	v_lshl_add_u64 v[174:175], v[174:175], 0, s[12:13]
	global_load_dwordx4 v[140:143], v[128:129], off
	global_load_dwordx4 v[136:139], v[128:129], off offset:256
	v_lshl_add_u64 v[128:129], v[172:173], 0, v[174:175]
	global_load_dwordx4 v[132:135], v[128:129], off
	s_nop 0
	global_load_dwordx4 v[128:131], v[128:129], off offset:256
	v_mov_b32_e32 v172, 0
	v_mov_b32_e32 v173, 0
	v_mov_b32_e32 v176, 0
	v_mov_b32_e32 v177, 0
	v_mov_b32_e32 v178, 0
	v_mov_b32_e32 v179, 0
	v_mov_b32_e32 v180, 0
	v_mov_b32_e32 v181, 0
	v_mov_b32_e32 v184, 0
	v_mov_b32_e32 v185, 0
	v_mov_b32_e32 v186, 0
	v_mov_b32_e32 v187, 0
	v_mov_b32_e32 v188, 0
	v_mov_b32_e32 v189, 0
	v_mov_b32_e32 v190, 0
	v_mov_b32_e32 v191, 0
	v_mov_b32_e32 v192, 0
	v_mov_b32_e32 v193, 0
	v_mov_b32_e32 v194, 0
	v_mov_b32_e32 v195, 0
	v_mov_b32_e32 v196, 0
	v_mov_b32_e32 v197, 0
	v_mov_b32_e32 v198, 0
	v_mov_b32_e32 v199, 0
	v_mov_b32_e32 v200, 0
	v_mov_b32_e32 v201, 0
	v_mov_b32_e32 v202, 0
	v_mov_b32_e32 v203, 0
	v_mov_b32_e32 v204, 0
	v_mov_b32_e32 v205, 0
	v_mov_b32_e32 v206, 0
	v_mov_b32_e32 v207, 0
	s_and_saveexec_b64 s[12:13], vcc
	s_cbranch_execz .LBB0_423
	s_mov_b64 s[30:31], 0x2800
	v_lshl_add_u64 v[180:181], v[170:171], 0, s[30:31]
	s_mov_b64 s[30:31], 0x3800
	v_lshl_add_u64 v[188:189], v[170:171], 0, s[30:31]
	s_mov_b64 s[30:31], 0x2c00
	v_lshl_add_u64 v[190:191], v[170:171], 0, s[30:31]
	s_mov_b64 s[30:31], 0x3c00
	v_lshl_add_u64 v[192:193], v[170:171], 0, s[30:31]
	global_load_dwordx4 v[170:173], v[180:181], off sc1
	global_load_dwordx4 v[176:179], v[188:189], off sc1
	global_load_dwordx4 v[184:187], v[190:191], off sc1
	global_load_dwordx4 v[208:211], v[192:193], off sc1
	s_waitcnt vmcnt(0)
	s_nop 0
	v_lshlrev_b32_e32 v204, 16, v170
	v_and_b32_e32 v205, 0xffff0000, v170
	v_lshlrev_b32_e32 v206, 16, v171
	v_and_b32_e32 v207, 0xffff0000, v171
	v_lshlrev_b32_e32 v200, 16, v172
	v_and_b32_e32 v201, 0xffff0000, v172
	v_lshlrev_b32_e32 v202, 16, v173
	v_and_b32_e32 v203, 0xffff0000, v173
	v_lshlrev_b32_e32 v196, 16, v176
	v_and_b32_e32 v197, 0xffff0000, v176
	v_lshlrev_b32_e32 v198, 16, v177
	v_and_b32_e32 v199, 0xffff0000, v177
	v_lshlrev_b32_e32 v192, 16, v178
	v_and_b32_e32 v193, 0xffff0000, v178
	v_lshlrev_b32_e32 v194, 16, v179
	v_and_b32_e32 v195, 0xffff0000, v179
	v_lshlrev_b32_e32 v188, 16, v184
	v_and_b32_e32 v189, 0xffff0000, v184
	v_lshlrev_b32_e32 v190, 16, v185
	v_and_b32_e32 v191, 0xffff0000, v185
	v_lshlrev_b32_e32 v184, 16, v186
	v_and_b32_e32 v185, 0xffff0000, v186
	v_lshlrev_b32_e32 v186, 16, v187
	v_and_b32_e32 v187, 0xffff0000, v187
	v_lshlrev_b32_e32 v178, 16, v208
	v_and_b32_e32 v179, 0xffff0000, v208
	v_lshlrev_b32_e32 v180, 16, v209
	v_and_b32_e32 v181, 0xffff0000, v209
	v_lshlrev_b32_e32 v172, 16, v210
	v_and_b32_e32 v173, 0xffff0000, v210
	v_lshlrev_b32_e32 v176, 16, v211
	v_and_b32_e32 v177, 0xffff0000, v211
.LBB0_423:
	s_or_b64 exec, exec, s[12:13]
	s_waitcnt vmcnt(3)
	s_and_saveexec_b64 s[12:13], s[8:9]
	v_lshl_add_u64 v[252:253], v[166:167], 2, s[6:7]
	global_atomic_add_f32 v[252:253], v250, off offset:512
	global_atomic_add_f32 v[252:253], v251, off offset:576
	s_or_b64 exec, exec, s[12:13]
	v_lshlrev_b32_e32 v208, 16, v140
	v_and_b32_e32 v209, 0xffff0000, v140
	v_lshlrev_b32_e32 v210, 16, v141
	v_and_b32_e32 v211, 0xffff0000, v141
	v_and_b32_e32 v245, 0xffff0000, v143
	v_pk_add_f32 v[140:141], v[44:45], v[204:205]
	v_pk_add_f32 v[170:171], v[42:43], v[202:203]
	v_lshlrev_b32_e32 v244, 16, v143
	v_fmac_f32_e32 v208, 0.5, v140
	v_fmac_f32_e32 v209, 0.5, v141
	v_cvt_pk_bf16_f32 v140, v208, v209
	v_fmac_f32_e32 v245, 0.5, v171
	v_and_b32_e32 v171, 0xffff0000, v140
	v_lshlrev_b32_e32 v214, 16, v142
	v_and_b32_e32 v215, 0xffff0000, v142
	v_pk_add_f32 v[142:143], v[46:47], v[206:207]
	v_pk_add_f32 v[200:201], v[40:41], v[200:201]
	v_fmac_f32_e32 v244, 0.5, v170
	v_lshlrev_b32_e32 v170, 16, v140
	v_mul_f32_e32 v206, v171, v171
	v_fmac_f32_e32 v210, 0.5, v142
	v_fmac_f32_e32 v211, 0.5, v143
	v_cvt_pk_bf16_f32 v141, v210, v211
	v_fmac_f32_e32 v214, 0.5, v200
	v_lshlrev_b32_e32 v200, 16, v141
	v_fmac_f32_e32 v206, v170, v170
	v_fmac_f32_e32 v215, 0.5, v201
	v_and_b32_e32 v201, 0xffff0000, v141
	v_fmac_f32_e32 v206, v200, v200
	v_cvt_pk_bf16_f32 v142, v214, v215
	v_fmac_f32_e32 v206, v201, v201
	v_lshlrev_b32_e32 v202, 16, v142
	v_and_b32_e32 v203, 0xffff0000, v142
	v_fmac_f32_e32 v206, v202, v202
	v_cvt_pk_bf16_f32 v143, v244, v245
	v_fmac_f32_e32 v206, v203, v203
	v_lshlrev_b32_e32 v204, 16, v143
	v_and_b32_e32 v205, 0xffff0000, v143
	v_fmac_f32_e32 v206, v204, v204
	v_fmac_f32_e32 v206, v205, v205
	s_waitcnt vmcnt(4)
	v_lshlrev_b32_e32 v200, 16, v136
	v_and_b32_e32 v201, 0xffff0000, v136
	v_lshlrev_b32_e32 v202, 16, v137
	v_and_b32_e32 v203, 0xffff0000, v137
	v_lshlrev_b32_e32 v204, 16, v138
	v_and_b32_e32 v205, 0xffff0000, v138
	v_lshlrev_b32_e32 v207, 16, v139
	v_and_b32_e32 v208, 0xffff0000, v139
	v_pk_add_f32 v[136:137], v[14:15], v[198:199]
	v_pk_add_f32 v[138:139], v[12:13], v[196:197]
	v_pk_add_f32 v[170:171], v[10:11], v[194:195]
	v_pk_add_f32 v[194:195], v[8:9], v[192:193]
	v_fmac_f32_e32 v200, 0.5, v138
	v_fmac_f32_e32 v201, 0.5, v139
	v_cvt_pk_bf16_f32 v192, v200, v201
	v_fmac_f32_e32 v202, 0.5, v136
	v_lshlrev_b32_e32 v136, 16, v192
	v_fmac_f32_e32 v203, 0.5, v137
	v_and_b32_e32 v137, 0xffff0000, v192
	v_fmac_f32_e32 v206, v136, v136
	v_cvt_pk_bf16_f32 v193, v202, v203
	v_fmac_f32_e32 v206, v137, v137
	v_lshlrev_b32_e32 v138, 16, v193
	v_and_b32_e32 v139, 0xffff0000, v193
	v_fmac_f32_e32 v206, v138, v138
	v_fmac_f32_e32 v204, 0.5, v194
	v_fmac_f32_e32 v205, 0.5, v195
	v_cvt_pk_bf16_f32 v194, v204, v205
	v_fmac_f32_e32 v207, 0.5, v170
	v_lshlrev_b32_e32 v170, 16, v194
	v_fmac_f32_e32 v206, v139, v139
	v_fmac_f32_e32 v208, 0.5, v171
	v_and_b32_e32 v171, 0xffff0000, v194
	v_fmac_f32_e32 v206, v170, v170
	v_cvt_pk_bf16_f32 v195, v207, v208
	v_fmac_f32_e32 v206, v171, v171
	v_lshlrev_b32_e32 v196, 16, v195
	v_and_b32_e32 v197, 0xffff0000, v195
	v_fmac_f32_e32 v206, v196, v196
	v_fmac_f32_e32 v206, v197, v197
	ds_bpermute_b32 v136, v237, v206
	v_lshl_add_u64 v[138:139], s[28:29], 0, v[182:183]
	v_lshl_add_u64 v[138:139], v[168:169], 1, v[138:139]
	global_store_dwordx4 v[138:139], v[140:143], off
	global_store_dwordx4 v[138:139], v[192:195], off offset:256
	s_waitcnt lgkmcnt(0)
	v_add_f32_e32 v136, v206, v136
	ds_bpermute_b32 v137, v238, v136
	s_and_saveexec_b64 s[12:13], s[8:9]
	s_cbranch_execz .LBB0_425
	s_waitcnt lgkmcnt(0)
	v_add_f32_e32 v138, v136, v137
	v_lshl_add_u64 v[136:137], v[166:167], 2, s[6:7]
	global_atomic_add_f32 v[136:137], v138, off offset:640
; DI unsigned cvt_pk(float lo, float hi) { unsigned r; asm("v_cvt_pk_bf16_f32 %0, %1, %2" : "=v"(r) : "v"(lo), "v"(hi)); return r; }
;     __device__ __forceinline__ void operator()(const f32x4 (&acc)[2][2][4][2], const Unit& u, int wr, int wc, int fr, int fq) const {
;     ...
; #pragma unroll
;                 for (int mm = 0; mm < 2; ++mm) {
;                     const int m = mp * 2 + mm;
;                     const int row = row0 + ai * HALF + m * 16;
;                     float s = 0.f;
; #pragma unroll
;                     for (int bj = 0; bj < 2; ++bj) {
;                         u32x4* px = (u32x4*)(X + (size_t)row * DM + col0 + bj * HALF);
;                         float xo[8]; unpack8(xin[mm][bj], xo);
;                         const f32x4 a0 = acc[ai][bj][m][0] + pv[mm][bj][0], a1 = acc[ai][bj][m][1] + pv[mm][bj][1];
;                         u32x4 w;
;                         w.x = cvt_pk(xo[0] + scale * a0[0], xo[1] + scale * a0[1]); w.y = cvt_pk(xo[2] + scale * a0[2], xo[3] + scale * a0[3]);
;                         w.z = cvt_pk(xo[4] + scale * a1[0], xo[5] + scale * a1[1]); w.w = cvt_pk(xo[6] + scale * a1[2], xo[7] + scale * a1[3]);
;                         *px = w;
;                         float xn[8]; unpack8(w, xn);
; #pragma unroll
;                         for (int j = 0; j < 8; ++j) s += xn[j] * xn[j];
;                     }
;                     s += __shfl_xor(s, 16); s += __shfl_xor(s, 32);
;                     if (fq == 0) unsafeAtomicAdd(ssn + row, s);
;                 }
.LBB0_425:
	s_or_b64 exec, exec, s[12:13]
	s_waitcnt vmcnt(5)
	v_lshlrev_b32_e32 v140, 16, v132
	v_and_b32_e32 v141, 0xffff0000, v132
	v_lshlrev_b32_e32 v142, 16, v133
	v_and_b32_e32 v143, 0xffff0000, v133
	v_lshlrev_b32_e32 v170, 16, v134
	v_and_b32_e32 v183, 0xffff0000, v135
	v_pk_add_f32 v[132:133], v[36:37], v[188:189]
	s_waitcnt lgkmcnt(0)
	v_pk_add_f32 v[136:137], v[34:35], v[186:187]
	v_pk_add_f32 v[138:139], v[32:33], v[184:185]
	v_and_b32_e32 v171, 0xffff0000, v134
	v_lshlrev_b32_e32 v182, 16, v135
	v_pk_add_f32 v[134:135], v[38:39], v[190:191]
	v_fmac_f32_e32 v140, 0.5, v132
	v_fmac_f32_e32 v141, 0.5, v133
	v_cvt_pk_bf16_f32 v132, v140, v141
	v_fmac_f32_e32 v170, 0.5, v138
	v_fmac_f32_e32 v183, 0.5, v137
	v_and_b32_e32 v137, 0xffff0000, v132
	v_fmac_f32_e32 v142, 0.5, v134
	v_fmac_f32_e32 v171, 0.5, v139
	v_cvt_pk_bf16_f32 v134, v170, v171
	v_fmac_f32_e32 v182, 0.5, v136
	v_lshlrev_b32_e32 v136, 16, v132
	v_mul_f32_e32 v170, v137, v137
	v_fmac_f32_e32 v143, 0.5, v135
	v_cvt_pk_bf16_f32 v133, v142, v143
	v_fmac_f32_e32 v170, v136, v136
	v_lshlrev_b32_e32 v138, 16, v133
	v_and_b32_e32 v139, 0xffff0000, v133
	v_fmac_f32_e32 v170, v138, v138
	v_lshlrev_b32_e32 v140, 16, v134
	v_fmac_f32_e32 v170, v139, v139
	v_and_b32_e32 v141, 0xffff0000, v134
	v_fmac_f32_e32 v170, v140, v140
	v_cvt_pk_bf16_f32 v135, v182, v183
	v_fmac_f32_e32 v170, v141, v141
	v_lshlrev_b32_e32 v142, 16, v135
	v_and_b32_e32 v143, 0xffff0000, v135
	v_fmac_f32_e32 v170, v142, v142
	s_waitcnt vmcnt(4)
	v_lshlrev_b32_e32 v136, 16, v128
	v_lshlrev_b32_e32 v171, 16, v130
	v_and_b32_e32 v182, 0xffff0000, v130
	v_lshlrev_b32_e32 v183, 16, v131
	v_and_b32_e32 v184, 0xffff0000, v131
	v_pk_add_f32 v[130:131], v[4:5], v[178:179]
	v_fmac_f32_e32 v170, v143, v143
	v_and_b32_e32 v137, 0xffff0000, v128
	v_lshlrev_b32_e32 v142, 16, v129
	v_and_b32_e32 v143, 0xffff0000, v129
	v_pk_add_f32 v[128:129], v[6:7], v[180:181]
	v_fmac_f32_e32 v136, 0.5, v130
	v_fmac_f32_e32 v137, 0.5, v131
	v_cvt_pk_bf16_f32 v136, v136, v137
	v_fmac_f32_e32 v142, 0.5, v128
	v_lshlrev_b32_e32 v128, 16, v136
	v_fmac_f32_e32 v143, 0.5, v129
	v_and_b32_e32 v129, 0xffff0000, v136
	v_fmac_f32_e32 v170, v128, v128
	v_cvt_pk_bf16_f32 v137, v142, v143
	v_fmac_f32_e32 v170, v129, v129
	v_lshlrev_b32_e32 v130, 16, v137
	v_pk_add_f32 v[140:141], v[2:3], v[176:177]
	v_pk_add_f32 v[138:139], v[0:1], v[172:173]
	v_and_b32_e32 v131, 0xffff0000, v137
	v_fmac_f32_e32 v170, v130, v130
	v_fmac_f32_e32 v171, 0.5, v138
	v_fmac_f32_e32 v182, 0.5, v139
	v_cvt_pk_bf16_f32 v138, v171, v182
	v_fmac_f32_e32 v183, 0.5, v140
	v_lshlrev_b32_e32 v140, 16, v138
	v_fmac_f32_e32 v170, v131, v131
	v_fmac_f32_e32 v184, 0.5, v141
	v_and_b32_e32 v141, 0xffff0000, v138
	v_fmac_f32_e32 v170, v140, v140
	v_cvt_pk_bf16_f32 v139, v183, v184
	v_fmac_f32_e32 v170, v141, v141
	v_lshlrev_b32_e32 v142, 16, v139
	v_and_b32_e32 v143, 0xffff0000, v139
	v_fmac_f32_e32 v170, v142, v142
	v_fmac_f32_e32 v170, v143, v143
	ds_bpermute_b32 v128, v237, v170
	v_lshl_add_u64 v[130:131], s[28:29], 0, v[174:175]
	v_lshl_add_u64 v[130:131], v[168:169], 1, v[130:131]
	global_store_dwordx4 v[130:131], v[132:135], off
	global_store_dwordx4 v[130:131], v[136:139], off offset:256
	s_waitcnt lgkmcnt(0)
	v_add_f32_e32 v128, v170, v128
	ds_bpermute_b32 v129, v238, v128
	s_and_saveexec_b64 s[12:13], s[8:9]
	s_cbranch_execz .LBB0_427
	s_waitcnt lgkmcnt(0)
	v_add_f32_e32 v130, v128, v129
	v_lshl_add_u64 v[128:129], v[166:167], 2, s[6:7]
	global_atomic_add_f32 v[128:129], v130, off offset:704

;     __device__ __forceinline__ void operator()(const f32x4 (&acc)[2][2][4][2], const Unit& u, int wr, int wc, int fr, int fq) const {
;     ...
;                 u32x4 xin[2][2];
; #pragma unroll
;                 for (int mm = 0; mm < 2; ++mm)
; #pragma unroll
;                     for (int bj = 0; bj < 2; ++bj) xin[mm][bj] = *(const u32x4*)(X + (size_t)(row0 + ai * HALF + (mp * 2 + mm) * 16) * DM + col0 + bj * HALF);
;                 f32x4 pv[2][2][2];
; #pragma unroll
;                 for (int mm = 0; mm < 2; ++mm)
; #pragma unroll
;                     for (int bj = 0; bj < 2; ++bj)
; #pragma unroll
;                         for (int n = 0; n < 2; ++n) pv[mm][bj][n] = (f32x4){0.f, 0.f, 0.f, 0.f};
;                 if (src) {
;                     u32x4 pc[2][2];
;     ...
;                     asm volatile("global_load_dwordx4 %0, %4, off sc1\n\tglobal_load_dwordx4 %1, %5, off sc1\n\tglobal_load_dwordx4 %2, %6, off sc1\n\tglobal_load_dwordx4 %3, %7, off sc1\n\ts_waitcnt vmcnt(0)"
;                                  : "=&v"(pc[0][0]), "=&v"(pc[0][1]), "=&v"(pc[1][0]), "=&v"(pc[1][1])
;                                  : "v"(src + CI(0, 0)), "v"(src + CI(0, 1)), "v"(src + CI(1, 0)), "v"(src + CI(1, 1))
;                                  : "memory");
;     ...
; #pragma unroll
;                     for (int mm = 0; mm < 2; ++mm)
; #pragma unroll
;                         for (int bj = 0; bj < 2; ++bj) { float f[8]; unpack8(pc[mm][bj], f); pv[mm][bj][0] = (f32x4){f[0], f[1], f[2], f[3]}; pv[mm][bj][1] = (f32x4){f[4], f[5], f[6], f[7]}; }
;                 }
; #pragma unroll
;                 for (int mm = 0; mm < 2; ++mm) {
;                     const int m = mp * 2 + mm;
;                     const int row = row0 + ai * HALF + m * 16;
;                     float s = 0.f;
; #pragma unroll
;                     for (int bj = 0; bj < 2; ++bj) {
;                         u32x4* px = (u32x4*)(X + (size_t)row * DM + col0 + bj * HALF);
;                         float xo[8]; unpack8(xin[mm][bj], xo);
;                         const f32x4 a0 = acc[ai][bj][m][0] + pv[mm][bj][0], a1 = acc[ai][bj][m][1] + pv[mm][bj][1];
;                         u32x4 w;
;                         w.x = cvt_pk(xo[0] + scale * a0[0], xo[1] + scale * a0[1]); w.y = cvt_pk(xo[2] + scale * a0[2], xo[3] + scale * a0[3]);
.LBB0_1161:
	s_or_b64 exec, exec, s[16:17]
	s_waitcnt vmcnt(0)
	v_lshlrev_b32_e32 v210, 16, v140
	v_and_b32_e32 v211, 0xffff0000, v140
	v_lshlrev_b32_e32 v214, 16, v141
	v_and_b32_e32 v215, 0xffff0000, v141
	v_pk_add_f32 v[140:141], v[124:125], v[206:207]
	v_lshlrev_b32_e32 v237, 16, v142
	v_and_b32_e32 v238, 0xffff0000, v142
	v_lshlrev_b32_e32 v244, 16, v143
	v_and_b32_e32 v245, 0xffff0000, v143
	v_pk_add_f32 v[142:143], v[126:127], v[208:209]
	v_add_f32_e32 v140, v140, v210
	v_add_f32_e32 v141, v141, v211
	v_pk_add_f32 v[202:203], v[120:121], v[202:203]
	v_cvt_pk_bf16_f32 v140, v140, v141
	v_add_f32_e32 v141, v142, v214
	v_add_f32_e32 v142, v143, v215
	v_pk_add_f32 v[204:205], v[122:123], v[204:205]
	v_cvt_pk_bf16_f32 v141, v141, v142
	v_add_f32_e32 v142, v202, v237
	v_add_f32_e32 v143, v203, v238
	v_cvt_pk_bf16_f32 v142, v142, v143
	v_add_f32_e32 v143, v204, v244
	v_add_f32_e32 v202, v205, v245
	v_and_b32_e32 v203, 0xffff0000, v140
	v_cvt_pk_bf16_f32 v143, v143, v202
	v_lshlrev_b32_e32 v202, 16, v140
	v_mul_f32_e32 v203, v203, v203
	v_lshlrev_b32_e32 v204, 16, v141
	v_fmac_f32_e32 v203, v202, v202
	v_and_b32_e32 v205, 0xffff0000, v141
	v_fmac_f32_e32 v203, v204, v204
	v_lshlrev_b32_e32 v206, 16, v142
	v_fmac_f32_e32 v203, v205, v205
	v_and_b32_e32 v207, 0xffff0000, v142
	v_fmac_f32_e32 v203, v206, v206
	v_lshlrev_b32_e32 v208, 16, v143
	v_fmac_f32_e32 v203, v207, v207
	v_and_b32_e32 v209, 0xffff0000, v143
	v_fmac_f32_e32 v203, v208, v208
	v_lshlrev_b32_e32 v202, 16, v136
	v_and_b32_e32 v204, 0xffff0000, v136
	v_lshlrev_b32_e32 v205, 16, v137
	v_and_b32_e32 v206, 0xffff0000, v137
	v_pk_add_f32 v[136:137], v[94:95], v[200:201]
	v_fmac_f32_e32 v203, v209, v209
	v_lshlrev_b32_e32 v207, 16, v138
	v_and_b32_e32 v208, 0xffff0000, v138
	v_lshlrev_b32_e32 v209, 16, v139
	v_and_b32_e32 v210, 0xffff0000, v139
	v_pk_add_f32 v[138:139], v[92:93], v[198:199]
	v_pk_add_f32 v[198:199], v[90:91], v[196:197]
	v_pk_add_f32 v[196:197], v[88:89], v[194:195]
	v_add_f32_e32 v136, v136, v205
	v_add_f32_e32 v137, v137, v206
	v_cvt_pk_bf16_f32 v195, v136, v137
	v_add_f32_e32 v136, v196, v207
	v_add_f32_e32 v137, v197, v208
	v_cvt_pk_bf16_f32 v196, v136, v137
	v_add_f32_e32 v136, v198, v209
	v_add_f32_e32 v138, v138, v202
	v_add_f32_e32 v139, v139, v204
	v_cvt_pk_bf16_f32 v194, v138, v139
	v_add_f32_e32 v137, v199, v210
	v_cvt_pk_bf16_f32 v197, v136, v137
	v_lshlrev_b32_e32 v136, 16, v194
	v_and_b32_e32 v137, 0xffff0000, v194
	v_fmac_f32_e32 v203, v136, v136
	v_lshlrev_b32_e32 v138, 16, v195
	v_fmac_f32_e32 v203, v137, v137
	v_and_b32_e32 v139, 0xffff0000, v195
	v_fmac_f32_e32 v203, v138, v138
	v_lshlrev_b32_e32 v198, 16, v196
	v_fmac_f32_e32 v203, v139, v139
	v_and_b32_e32 v137, 64, v221
	v_and_b32_e32 v199, 0xffff0000, v196
	v_fmac_f32_e32 v203, v198, v198
	v_xor_b32_e32 v136, 16, v221
	v_add_u32_e32 v137, 64, v137
	v_lshlrev_b32_e32 v200, 16, v197
	v_fmac_f32_e32 v203, v199, v199
	v_cmp_lt_i32_e64 s[16:17], v136, v137
	v_and_b32_e32 v201, 0xffff0000, v197
	v_fmac_f32_e32 v203, v200, v200
	v_cndmask_b32_e64 v136, v221, v136, s[16:17]
	v_fmac_f32_e32 v203, v201, v201
	v_lshlrev_b32_e32 v237, 2, v136
	ds_bpermute_b32 v136, v237, v203
	v_xor_b32_e32 v138, 32, v221
	v_cmp_lt_i32_e64 s[16:17], v138, v137
	s_waitcnt lgkmcnt(0)
	v_add_f32_e32 v136, v203, v136
	v_cndmask_b32_e64 v137, v221, v138, s[16:17]
	v_lshlrev_b32_e32 v238, 2, v137
	ds_bpermute_b32 v137, v238, v136
	v_lshl_add_u64 v[138:139], s[36:37], 0, v[174:175]
	v_lshl_add_u64 v[138:139], v[168:169], 1, v[138:139]
	global_store_dwordx4 v[138:139], v[140:143], off
	global_store_dwordx4 v[138:139], v[194:197], off offset:256
	s_waitcnt lgkmcnt(0)
	v_add_f32_e32 v250, v136, v137
.LBB0_1163:
	v_lshlrev_b32_e32 v140, 16, v132
	v_and_b32_e32 v141, 0xffff0000, v132
	v_lshlrev_b32_e32 v142, 16, v133
	v_and_b32_e32 v143, 0xffff0000, v133
	v_pk_add_f32 v[132:133], v[116:117], v[190:191]
	v_lshlrev_b32_e32 v194, 16, v134
	v_and_b32_e32 v195, 0xffff0000, v134
	v_lshlrev_b32_e32 v196, 16, v135
	v_and_b32_e32 v197, 0xffff0000, v135
	v_pk_add_f32 v[134:135], v[118:119], v[192:193]
	v_add_f32_e32 v132, v132, v140
	v_add_f32_e32 v133, v133, v141
	v_pk_add_f32 v[138:139], v[112:113], v[186:187]
	v_cvt_pk_bf16_f32 v132, v132, v133
	v_add_f32_e32 v133, v134, v142
	v_add_f32_e32 v134, v135, v143
	s_waitcnt lgkmcnt(0)
	v_pk_add_f32 v[136:137], v[114:115], v[188:189]
	v_cvt_pk_bf16_f32 v133, v133, v134
	v_add_f32_e32 v134, v138, v194
	v_add_f32_e32 v135, v139, v195
	v_cvt_pk_bf16_f32 v134, v134, v135
	v_add_f32_e32 v135, v136, v196
	v_add_f32_e32 v136, v137, v197
	v_and_b32_e32 v137, 0xffff0000, v132
	v_cvt_pk_bf16_f32 v135, v135, v136
	v_lshlrev_b32_e32 v136, 16, v132
	v_mul_f32_e32 v186, v137, v137
	v_lshlrev_b32_e32 v138, 16, v133
	v_fmac_f32_e32 v186, v136, v136
	v_and_b32_e32 v139, 0xffff0000, v133
	v_fmac_f32_e32 v186, v138, v138
	v_lshlrev_b32_e32 v140, 16, v134
	v_fmac_f32_e32 v186, v139, v139
	v_and_b32_e32 v141, 0xffff0000, v134
	v_fmac_f32_e32 v186, v140, v140
	v_lshlrev_b32_e32 v142, 16, v135
	v_fmac_f32_e32 v186, v141, v141
	v_and_b32_e32 v143, 0xffff0000, v135
	v_fmac_f32_e32 v186, v142, v142
	v_fmac_f32_e32 v186, v143, v143
	v_lshlrev_b32_e32 v136, 16, v128
	v_and_b32_e32 v137, 0xffff0000, v128
	v_lshlrev_b32_e32 v142, 16, v129
	v_and_b32_e32 v143, 0xffff0000, v129
	v_pk_add_f32 v[128:129], v[86:87], v[184:185]
	v_lshlrev_b32_e32 v187, 16, v130
	v_and_b32_e32 v188, 0xffff0000, v130
	v_lshlrev_b32_e32 v189, 16, v131
	v_and_b32_e32 v190, 0xffff0000, v131
	v_pk_add_f32 v[130:131], v[84:85], v[182:183]
	v_pk_add_f32 v[138:139], v[80:81], v[178:179]
	v_add_f32_e32 v128, v128, v142
	v_pk_add_f32 v[140:141], v[82:83], v[180:181]
	v_add_f32_e32 v131, v131, v137
	v_add_f32_e32 v129, v129, v143
	v_cvt_pk_bf16_f32 v137, v128, v129
	v_add_f32_e32 v128, v138, v187
	v_add_f32_e32 v129, v139, v188
	v_cvt_pk_bf16_f32 v138, v128, v129
	v_add_f32_e32 v128, v140, v189
	v_add_f32_e32 v130, v130, v136
	v_cvt_pk_bf16_f32 v136, v130, v131
	v_add_f32_e32 v129, v141, v190
	v_cvt_pk_bf16_f32 v139, v128, v129
	v_lshlrev_b32_e32 v128, 16, v136
	v_and_b32_e32 v129, 0xffff0000, v136
	v_fmac_f32_e32 v186, v128, v128
	v_lshlrev_b32_e32 v130, 16, v137
	v_fmac_f32_e32 v186, v129, v129
	v_and_b32_e32 v131, 0xffff0000, v137
	v_fmac_f32_e32 v186, v130, v130
	v_lshlrev_b32_e32 v140, 16, v138
	v_fmac_f32_e32 v186, v131, v131
	v_and_b32_e32 v141, 0xffff0000, v138
	v_fmac_f32_e32 v186, v140, v140
	v_lshlrev_b32_e32 v142, 16, v139
	v_fmac_f32_e32 v186, v141, v141
	v_and_b32_e32 v143, 0xffff0000, v139
	v_fmac_f32_e32 v186, v142, v142
	v_fmac_f32_e32 v186, v143, v143
	ds_bpermute_b32 v128, v237, v186
	v_lshl_add_u64 v[130:131], s[36:37], 0, v[176:177]
	v_lshl_add_u64 v[130:131], v[168:169], 1, v[130:131]
	global_store_dwordx4 v[130:131], v[132:135], off
	global_store_dwordx4 v[130:131], v[136:139], off offset:256
	s_waitcnt lgkmcnt(0)
	v_add_f32_e32 v128, v186, v128
	ds_bpermute_b32 v129, v238, v128
	s_waitcnt lgkmcnt(0)
	v_add_f32_e32 v251, v128, v129
;     __device__ __forceinline__ void operator()(const f32x4 (&acc)[2][2][4][2], const Unit& u, int wr, int wc, int fr, int fq) const {
;     ...
;                 u32x4 xin[2][2];
; #pragma unroll
;                 for (int mm = 0; mm < 2; ++mm)
; #pragma unroll
;                     for (int bj = 0; bj < 2; ++bj) xin[mm][bj] = *(const u32x4*)(X + (size_t)(row0 + ai * HALF + (mp * 2 + mm) * 16) * DM + col0 + bj * HALF);
;                 f32x4 pv[2][2][2];
; #pragma unroll
;                 for (int mm = 0; mm < 2; ++mm)
; #pragma unroll
;                     for (int bj = 0; bj < 2; ++bj)
; #pragma unroll
;                         for (int n = 0; n < 2; ++n) pv[mm][bj][n] = (f32x4){0.f, 0.f, 0.f, 0.f};
;                 if (src) {
;                     u32x4 pc[2][2];
;     ...
;                     asm volatile("global_load_dwordx4 %0, %4, off sc1\n\tglobal_load_dwordx4 %1, %5, off sc1\n\tglobal_load_dwordx4 %2, %6, off sc1\n\tglobal_load_dwordx4 %3, %7, off sc1\n\ts_waitcnt vmcnt(0)"
;                                  : "=&v"(pc[0][0]), "=&v"(pc[0][1]), "=&v"(pc[1][0]), "=&v"(pc[1][1])
;                                  : "v"(src + CI(0, 0)), "v"(src + CI(0, 1)), "v"(src + CI(1, 0)), "v"(src + CI(1, 1))
;                                  : "memory");
;     ...
; #pragma unroll
;                     for (int mm = 0; mm < 2; ++mm)
; #pragma unroll
;                         for (int bj = 0; bj < 2; ++bj) { float f[8]; unpack8(pc[mm][bj], f); pv[mm][bj][0] = (f32x4){f[0], f[1], f[2], f[3]}; pv[mm][bj][1] = (f32x4){f[4], f[5], f[6], f[7]}; }
;                 }
; #pragma unroll
;                 for (int mm = 0; mm < 2; ++mm) {
;                     const int m = mp * 2 + mm;
;                     const int row = row0 + ai * HALF + m * 16;
;                     float s = 0.f;
; #pragma unroll
;                     for (int bj = 0; bj < 2; ++bj) {
;                         u32x4* px = (u32x4*)(X + (size_t)row * DM + col0 + bj * HALF);
;                         float xo[8]; unpack8(xin[mm][bj], xo);
;                         const f32x4 a0 = acc[ai][bj][m][0] + pv[mm][bj][0], a1 = acc[ai][bj][m][1] + pv[mm][bj][1];
;                         u32x4 w;
;                         w.x = cvt_pk(xo[0] + scale * a0[0], xo[1] + scale * a0[1]); w.y = cvt_pk(xo[2] + scale * a0[2], xo[3] + scale * a0[3]);
.LBB0_1165:
	v_or_b32_e32 v128, 32, v166
	s_waitcnt lgkmcnt(0)
	v_ashrrev_i32_e32 v129, 31, v128
	v_lshlrev_b64 v[186:187], 11, v[128:129]
	v_lshl_add_u64 v[128:129], v[172:173], 0, v[186:187]
	global_load_dwordx4 v[140:143], v[128:129], off
	global_load_dwordx4 v[136:139], v[128:129], off offset:256
	v_or_b32_e32 v128, 48, v166
	v_ashrrev_i32_e32 v129, 31, v128
	v_lshlrev_b64 v[176:177], 11, v[128:129]
	v_lshl_add_u64 v[128:129], v[172:173], 0, v[176:177]
	global_load_dwordx4 v[132:135], v[128:129], off
	s_nop 0
	global_load_dwordx4 v[128:131], v[128:129], off offset:256
	v_mov_b32_e32 v178, 0
	v_mov_b32_e32 v179, 0
	v_mov_b32_e32 v180, 0
	v_mov_b32_e32 v181, 0
	v_mov_b32_e32 v182, 0
	v_mov_b32_e32 v183, 0
	v_mov_b32_e32 v184, 0
	v_mov_b32_e32 v185, 0
	v_mov_b32_e32 v188, 0
	v_mov_b32_e32 v189, 0
	v_mov_b32_e32 v190, 0
	v_mov_b32_e32 v191, 0
	v_mov_b32_e32 v192, 0
	v_mov_b32_e32 v193, 0
	v_mov_b32_e32 v194, 0
	v_mov_b32_e32 v195, 0
	v_mov_b32_e32 v196, 0
	v_mov_b32_e32 v197, 0
	v_mov_b32_e32 v198, 0
	v_mov_b32_e32 v199, 0
	v_mov_b32_e32 v200, 0
	v_mov_b32_e32 v201, 0
	v_mov_b32_e32 v202, 0
	v_mov_b32_e32 v203, 0
	v_mov_b32_e32 v204, 0
	v_mov_b32_e32 v205, 0
	v_mov_b32_e32 v206, 0
	v_mov_b32_e32 v207, 0
	v_mov_b32_e32 v208, 0
	v_mov_b32_e32 v209, 0
	v_mov_b32_e32 v210, 0
	v_mov_b32_e32 v211, 0
	s_and_saveexec_b64 s[16:17], vcc
	s_cbranch_execz .LBB0_1167
	s_mov_b64 s[38:39], 0x800
	v_lshl_add_u64 v[192:193], v[170:171], 0, s[38:39]
	s_mov_b64 s[38:39], 0x1800
	v_lshl_add_u64 v[194:195], v[170:171], 0, s[38:39]
	s_mov_b64 s[38:39], 0xc00
	v_lshl_add_u64 v[196:197], v[170:171], 0, s[38:39]
	s_mov_b64 s[38:39], 0x1c00
	v_lshl_add_u64 v[198:199], v[170:171], 0, s[38:39]
	global_load_dwordx4 v[178:181], v[192:193], off sc1
	global_load_dwordx4 v[182:185], v[194:195], off sc1
	global_load_dwordx4 v[188:191], v[196:197], off sc1
	global_load_dwordx4 v[244:247], v[198:199], off sc1
	s_waitcnt vmcnt(0)
	s_nop 0
	v_lshlrev_b32_e32 v208, 16, v178
	v_and_b32_e32 v209, 0xffff0000, v178
	v_lshlrev_b32_e32 v210, 16, v179
	v_and_b32_e32 v211, 0xffff0000, v179
	v_lshlrev_b32_e32 v204, 16, v180
	v_and_b32_e32 v205, 0xffff0000, v180
	v_lshlrev_b32_e32 v206, 16, v181
	v_and_b32_e32 v207, 0xffff0000, v181
	v_lshlrev_b32_e32 v200, 16, v182
	v_and_b32_e32 v201, 0xffff0000, v182
	v_lshlrev_b32_e32 v202, 16, v183
	v_and_b32_e32 v203, 0xffff0000, v183
	v_lshlrev_b32_e32 v196, 16, v184
	v_and_b32_e32 v197, 0xffff0000, v184
	v_lshlrev_b32_e32 v198, 16, v185
	v_and_b32_e32 v199, 0xffff0000, v185
	v_lshlrev_b32_e32 v192, 16, v188
	v_and_b32_e32 v193, 0xffff0000, v188
	v_lshlrev_b32_e32 v194, 16, v189
	v_and_b32_e32 v195, 0xffff0000, v189
	v_lshlrev_b32_e32 v188, 16, v190
	v_and_b32_e32 v189, 0xffff0000, v190
	v_lshlrev_b32_e32 v190, 16, v191
	v_and_b32_e32 v191, 0xffff0000, v191
	v_lshlrev_b32_e32 v182, 16, v244
	v_and_b32_e32 v183, 0xffff0000, v244
	v_lshlrev_b32_e32 v184, 16, v245
	v_and_b32_e32 v185, 0xffff0000, v245
	v_lshlrev_b32_e32 v178, 16, v246
	v_and_b32_e32 v179, 0xffff0000, v246
	v_lshlrev_b32_e32 v180, 16, v247
	v_and_b32_e32 v181, 0xffff0000, v247
.LBB0_1167:
	s_or_b64 exec, exec, s[16:17]
	s_waitcnt vmcnt(3)
	s_and_saveexec_b64 s[16:17], s[12:13]
	v_lshl_add_u64 v[252:253], v[166:167], 2, s[4:5]
	global_atomic_add_f32 v[252:253], v250, off
	global_atomic_add_f32 v[252:253], v251, off offset:64
	s_or_b64 exec, exec, s[16:17]
	v_lshlrev_b32_e32 v214, 16, v140
	v_and_b32_e32 v215, 0xffff0000, v140
	v_lshlrev_b32_e32 v244, 16, v141
	v_and_b32_e32 v245, 0xffff0000, v141
	v_pk_add_f32 v[140:141], v[108:109], v[208:209]
	v_lshlrev_b32_e32 v246, 16, v142
	v_and_b32_e32 v247, 0xffff0000, v142
	v_lshlrev_b32_e32 v248, 16, v143
	v_and_b32_e32 v249, 0xffff0000, v143
	v_pk_add_f32 v[142:143], v[110:111], v[210:211]
	v_add_f32_e32 v140, v140, v214
	v_add_f32_e32 v141, v141, v215
	v_pk_add_f32 v[204:205], v[104:105], v[204:205]
	v_cvt_pk_bf16_f32 v140, v140, v141
	v_add_f32_e32 v141, v142, v244
	v_add_f32_e32 v142, v143, v245
	v_pk_add_f32 v[206:207], v[106:107], v[206:207]
	v_cvt_pk_bf16_f32 v141, v141, v142
	v_add_f32_e32 v142, v204, v246
	v_add_f32_e32 v143, v205, v247
	v_cvt_pk_bf16_f32 v142, v142, v143
	v_add_f32_e32 v143, v206, v248
	v_add_f32_e32 v204, v207, v249
	v_and_b32_e32 v205, 0xffff0000, v140
	v_cvt_pk_bf16_f32 v143, v143, v204
	v_lshlrev_b32_e32 v204, 16, v140
	v_mul_f32_e32 v205, v205, v205
	v_lshlrev_b32_e32 v206, 16, v141
	v_fmac_f32_e32 v205, v204, v204
	v_and_b32_e32 v207, 0xffff0000, v141
	v_fmac_f32_e32 v205, v206, v206
	v_lshlrev_b32_e32 v208, 16, v142
	v_fmac_f32_e32 v205, v207, v207
	v_and_b32_e32 v209, 0xffff0000, v142
	v_fmac_f32_e32 v205, v208, v208
	v_lshlrev_b32_e32 v210, 16, v143
	v_fmac_f32_e32 v205, v209, v209
	v_and_b32_e32 v211, 0xffff0000, v143
	v_fmac_f32_e32 v205, v210, v210
	s_waitcnt vmcnt(4)
	v_lshlrev_b32_e32 v204, 16, v136
	v_and_b32_e32 v206, 0xffff0000, v136
	v_lshlrev_b32_e32 v207, 16, v137
	v_and_b32_e32 v208, 0xffff0000, v137
	v_pk_add_f32 v[136:137], v[78:79], v[202:203]
	v_fmac_f32_e32 v205, v211, v211
	v_lshlrev_b32_e32 v209, 16, v138
	v_and_b32_e32 v210, 0xffff0000, v138
	v_lshlrev_b32_e32 v211, 16, v139
	v_and_b32_e32 v214, 0xffff0000, v139
	v_pk_add_f32 v[138:139], v[76:77], v[200:201]
	v_pk_add_f32 v[200:201], v[74:75], v[198:199]
	v_pk_add_f32 v[198:199], v[72:73], v[196:197]
	v_add_f32_e32 v136, v136, v207
	v_add_f32_e32 v137, v137, v208
	v_cvt_pk_bf16_f32 v197, v136, v137
	v_add_f32_e32 v136, v198, v209
	v_add_f32_e32 v137, v199, v210
	v_cvt_pk_bf16_f32 v198, v136, v137
	v_add_f32_e32 v136, v200, v211
	v_add_f32_e32 v138, v138, v204
	v_add_f32_e32 v139, v139, v206
	v_cvt_pk_bf16_f32 v196, v138, v139
	v_add_f32_e32 v137, v201, v214
	v_cvt_pk_bf16_f32 v199, v136, v137
	v_lshlrev_b32_e32 v136, 16, v196
	v_and_b32_e32 v137, 0xffff0000, v196
	v_fmac_f32_e32 v205, v136, v136
	v_lshlrev_b32_e32 v138, 16, v197
	v_fmac_f32_e32 v205, v137, v137
	v_and_b32_e32 v139, 0xffff0000, v197
	v_fmac_f32_e32 v205, v138, v138
	v_lshlrev_b32_e32 v200, 16, v198
	v_fmac_f32_e32 v205, v139, v139
	v_and_b32_e32 v201, 0xffff0000, v198
	v_fmac_f32_e32 v205, v200, v200
	v_lshlrev_b32_e32 v202, 16, v199
	v_fmac_f32_e32 v205, v201, v201
	v_and_b32_e32 v203, 0xffff0000, v199
	v_fmac_f32_e32 v205, v202, v202
	v_fmac_f32_e32 v205, v203, v203
	ds_bpermute_b32 v136, v237, v205
	v_lshl_add_u64 v[138:139], s[36:37], 0, v[186:187]
	v_lshl_add_u64 v[138:139], v[168:169], 1, v[138:139]
	global_store_dwordx4 v[138:139], v[140:143], off
	global_store_dwordx4 v[138:139], v[196:199], off offset:256
	s_waitcnt lgkmcnt(0)
	v_add_f32_e32 v136, v205, v136
	ds_bpermute_b32 v137, v238, v136
	s_waitcnt lgkmcnt(0)
	v_add_f32_e32 v250, v136, v137
;     __device__ __forceinline__ void operator()(const f32x4 (&acc)[2][2][4][2], const Unit& u, int wr, int wc, int fr, int fq) const {
;     ...
;                 u32x4 xin[2][2];
; #pragma unroll
;                 for (int mm = 0; mm < 2; ++mm)
; #pragma unroll
;                     for (int bj = 0; bj < 2; ++bj) xin[mm][bj] = *(const u32x4*)(X + (size_t)(row0 + ai * HALF + (mp * 2 + mm) * 16) * DM + col0 + bj * HALF);
;                 f32x4 pv[2][2][2];
; #pragma unroll
;                 for (int mm = 0; mm < 2; ++mm)
; #pragma unroll
;                     for (int bj = 0; bj < 2; ++bj)
; #pragma unroll
;                         for (int n = 0; n < 2; ++n) pv[mm][bj][n] = (f32x4){0.f, 0.f, 0.f, 0.f};
;                 if (src) {
;                     u32x4 pc[2][2];
;     ...
;                     asm volatile("global_load_dwordx4 %0, %4, off sc1\n\tglobal_load_dwordx4 %1, %5, off sc1\n\tglobal_load_dwordx4 %2, %6, off sc1\n\tglobal_load_dwordx4 %3, %7, off sc1\n\ts_waitcnt vmcnt(0)"
;                                  : "=&v"(pc[0][0]), "=&v"(pc[0][1]), "=&v"(pc[1][0]), "=&v"(pc[1][1])
;                                  : "v"(src + CI(0, 0)), "v"(src + CI(0, 1)), "v"(src + CI(1, 0)), "v"(src + CI(1, 1))
;                                  : "memory");
;     ...
; #pragma unroll
;                     for (int mm = 0; mm < 2; ++mm)
; #pragma unroll
;                         for (int bj = 0; bj < 2; ++bj) { float f[8]; unpack8(pc[mm][bj], f); pv[mm][bj][0] = (f32x4){f[0], f[1], f[2], f[3]}; pv[mm][bj][1] = (f32x4){f[4], f[5], f[6], f[7]}; }
;                 }
; #pragma unroll
;                 for (int mm = 0; mm < 2; ++mm) {
;                     const int m = mp * 2 + mm;
;                     const int row = row0 + ai * HALF + m * 16;
;                     float s = 0.f;
; #pragma unroll
;                     for (int bj = 0; bj < 2; ++bj) {
;                         u32x4* px = (u32x4*)(X + (size_t)row * DM + col0 + bj * HALF);
;                         float xo[8]; unpack8(xin[mm][bj], xo);
;                         const f32x4 a0 = acc[ai][bj][m][0] + pv[mm][bj][0], a1 = acc[ai][bj][m][1] + pv[mm][bj][1];
;                         u32x4 w;
;                         w.x = cvt_pk(xo[0] + scale * a0[0], xo[1] + scale * a0[1]); w.y = cvt_pk(xo[2] + scale * a0[2], xo[3] + scale * a0[3]);
.LBB0_1169:
	s_waitcnt vmcnt(5)
	v_lshlrev_b32_e32 v140, 16, v132
	v_and_b32_e32 v141, 0xffff0000, v132
	v_lshlrev_b32_e32 v142, 16, v133
	v_and_b32_e32 v143, 0xffff0000, v133
	v_pk_add_f32 v[132:133], v[100:101], v[192:193]
	v_lshlrev_b32_e32 v186, 16, v134
	v_and_b32_e32 v187, 0xffff0000, v134
	v_lshlrev_b32_e32 v196, 16, v135
	v_and_b32_e32 v197, 0xffff0000, v135
	v_pk_add_f32 v[134:135], v[102:103], v[194:195]
	v_add_f32_e32 v132, v132, v140
	v_add_f32_e32 v133, v133, v141
	v_pk_add_f32 v[138:139], v[96:97], v[188:189]
	v_cvt_pk_bf16_f32 v132, v132, v133
	v_add_f32_e32 v133, v134, v142
	v_add_f32_e32 v134, v135, v143
	s_waitcnt lgkmcnt(0)
	v_pk_add_f32 v[136:137], v[98:99], v[190:191]
	v_cvt_pk_bf16_f32 v133, v133, v134
	v_add_f32_e32 v134, v138, v186
	v_add_f32_e32 v135, v139, v187
	v_cvt_pk_bf16_f32 v134, v134, v135
	v_add_f32_e32 v135, v136, v196
	v_add_f32_e32 v136, v137, v197
	v_and_b32_e32 v137, 0xffff0000, v132
	v_cvt_pk_bf16_f32 v135, v135, v136
	v_lshlrev_b32_e32 v136, 16, v132
	v_mul_f32_e32 v186, v137, v137
	v_lshlrev_b32_e32 v138, 16, v133
	v_fmac_f32_e32 v186, v136, v136
	v_and_b32_e32 v139, 0xffff0000, v133
	v_fmac_f32_e32 v186, v138, v138
	v_lshlrev_b32_e32 v140, 16, v134
	v_fmac_f32_e32 v186, v139, v139
	v_and_b32_e32 v141, 0xffff0000, v134
	v_fmac_f32_e32 v186, v140, v140
	v_lshlrev_b32_e32 v142, 16, v135
	v_fmac_f32_e32 v186, v141, v141
	v_and_b32_e32 v143, 0xffff0000, v135
	v_fmac_f32_e32 v186, v142, v142
	v_fmac_f32_e32 v186, v143, v143
	s_waitcnt vmcnt(4)
	v_lshlrev_b32_e32 v136, 16, v128
	v_and_b32_e32 v137, 0xffff0000, v128
	v_lshlrev_b32_e32 v142, 16, v129
	v_and_b32_e32 v143, 0xffff0000, v129
	v_pk_add_f32 v[128:129], v[70:71], v[184:185]
	v_lshlrev_b32_e32 v187, 16, v130
	v_and_b32_e32 v188, 0xffff0000, v130
	v_lshlrev_b32_e32 v189, 16, v131
	v_and_b32_e32 v190, 0xffff0000, v131
	v_pk_add_f32 v[130:131], v[68:69], v[182:183]
	v_pk_add_f32 v[138:139], v[64:65], v[178:179]
	v_add_f32_e32 v128, v128, v142
	v_pk_add_f32 v[140:141], v[66:67], v[180:181]
	v_add_f32_e32 v131, v131, v137
	v_add_f32_e32 v129, v129, v143
	v_cvt_pk_bf16_f32 v137, v128, v129
	v_add_f32_e32 v128, v138, v187
	v_add_f32_e32 v129, v139, v188
	v_cvt_pk_bf16_f32 v138, v128, v129
	v_add_f32_e32 v128, v140, v189
	v_add_f32_e32 v130, v130, v136
	v_cvt_pk_bf16_f32 v136, v130, v131
	v_add_f32_e32 v129, v141, v190
	v_cvt_pk_bf16_f32 v139, v128, v129
	v_lshlrev_b32_e32 v128, 16, v136
	v_and_b32_e32 v129, 0xffff0000, v136
	v_fmac_f32_e32 v186, v128, v128
	v_lshlrev_b32_e32 v130, 16, v137
	v_fmac_f32_e32 v186, v129, v129
	v_and_b32_e32 v131, 0xffff0000, v137
	v_fmac_f32_e32 v186, v130, v130
	v_lshlrev_b32_e32 v140, 16, v138
	v_fmac_f32_e32 v186, v131, v131
	v_and_b32_e32 v141, 0xffff0000, v138
	v_fmac_f32_e32 v186, v140, v140
	v_lshlrev_b32_e32 v142, 16, v139
	v_fmac_f32_e32 v186, v141, v141
	v_and_b32_e32 v143, 0xffff0000, v139
	v_fmac_f32_e32 v186, v142, v142
	v_fmac_f32_e32 v186, v143, v143
	ds_bpermute_b32 v128, v237, v186
	v_lshl_add_u64 v[130:131], s[36:37], 0, v[176:177]
	v_lshl_add_u64 v[130:131], v[168:169], 1, v[130:131]
	global_store_dwordx4 v[130:131], v[132:135], off
	global_store_dwordx4 v[130:131], v[136:139], off offset:256
	s_waitcnt lgkmcnt(0)
	v_add_f32_e32 v128, v186, v128
	ds_bpermute_b32 v129, v238, v128
	s_waitcnt lgkmcnt(0)
	v_add_f32_e32 v251, v128, v129
.LBB0_1171:
	s_mov_b64 s[16:17], 0x40000
	v_lshl_add_u64 v[186:187], v[174:175], 0, s[16:17]
	s_mov_b64 s[16:17], 0x48000
	s_waitcnt lgkmcnt(0)
	v_lshl_add_u64 v[128:129], v[172:173], 0, v[186:187]
	v_lshl_add_u64 v[176:177], v[174:175], 0, s[16:17]
	global_load_dwordx4 v[140:143], v[128:129], off
	global_load_dwordx4 v[136:139], v[128:129], off offset:256
	v_lshl_add_u64 v[128:129], v[172:173], 0, v[176:177]
	global_load_dwordx4 v[132:135], v[128:129], off
	s_nop 0
	global_load_dwordx4 v[128:131], v[128:129], off offset:256
	v_mov_b32_e32 v178, 0
	v_mov_b32_e32 v179, 0
	v_mov_b32_e32 v180, 0
	v_mov_b32_e32 v181, 0
	v_mov_b32_e32 v182, 0
	v_mov_b32_e32 v183, 0
	v_mov_b32_e32 v184, 0
	v_mov_b32_e32 v185, 0
	v_mov_b32_e32 v188, 0
	v_mov_b32_e32 v189, 0
	v_mov_b32_e32 v190, 0
	v_mov_b32_e32 v191, 0
	v_mov_b32_e32 v192, 0
	v_mov_b32_e32 v193, 0
	v_mov_b32_e32 v194, 0
	v_mov_b32_e32 v195, 0
	v_mov_b32_e32 v196, 0
	v_mov_b32_e32 v197, 0
	v_mov_b32_e32 v198, 0
	v_mov_b32_e32 v199, 0
	v_mov_b32_e32 v200, 0
	v_mov_b32_e32 v201, 0
	v_mov_b32_e32 v202, 0
	v_mov_b32_e32 v203, 0
	v_mov_b32_e32 v204, 0
	v_mov_b32_e32 v205, 0
	v_mov_b32_e32 v206, 0
	v_mov_b32_e32 v207, 0
	v_mov_b32_e32 v208, 0
	v_mov_b32_e32 v209, 0
	v_mov_b32_e32 v210, 0
	v_mov_b32_e32 v211, 0
	s_and_saveexec_b64 s[16:17], vcc
	s_cbranch_execz .LBB0_1173
	s_mov_b64 s[38:39], 0x2000
	v_lshl_add_u64 v[192:193], v[170:171], 0, s[38:39]
	s_mov_b64 s[38:39], 0x3000
	v_lshl_add_u64 v[194:195], v[170:171], 0, s[38:39]
	s_mov_b64 s[38:39], 0x2400
	v_lshl_add_u64 v[196:197], v[170:171], 0, s[38:39]
	s_mov_b64 s[38:39], 0x3400
	v_lshl_add_u64 v[198:199], v[170:171], 0, s[38:39]
	global_load_dwordx4 v[178:181], v[192:193], off sc1
	global_load_dwordx4 v[182:185], v[194:195], off sc1
	global_load_dwordx4 v[188:191], v[196:197], off sc1
	global_load_dwordx4 v[244:247], v[198:199], off sc1
	s_waitcnt vmcnt(0)
	s_nop 0
	v_lshlrev_b32_e32 v208, 16, v178
	v_and_b32_e32 v209, 0xffff0000, v178
	v_lshlrev_b32_e32 v210, 16, v179
	v_and_b32_e32 v211, 0xffff0000, v179
	v_lshlrev_b32_e32 v204, 16, v180
	v_and_b32_e32 v205, 0xffff0000, v180
	v_lshlrev_b32_e32 v206, 16, v181
	v_and_b32_e32 v207, 0xffff0000, v181
	v_lshlrev_b32_e32 v200, 16, v182
	v_and_b32_e32 v201, 0xffff0000, v182
	v_lshlrev_b32_e32 v202, 16, v183
	v_and_b32_e32 v203, 0xffff0000, v183
	v_lshlrev_b32_e32 v196, 16, v184
	v_and_b32_e32 v197, 0xffff0000, v184
	v_lshlrev_b32_e32 v198, 16, v185
	v_and_b32_e32 v199, 0xffff0000, v185
	v_lshlrev_b32_e32 v192, 16, v188
	v_and_b32_e32 v193, 0xffff0000, v188
	v_lshlrev_b32_e32 v194, 16, v189
	v_and_b32_e32 v195, 0xffff0000, v189
	v_lshlrev_b32_e32 v188, 16, v190
	v_and_b32_e32 v189, 0xffff0000, v190
	v_lshlrev_b32_e32 v190, 16, v191
	v_and_b32_e32 v191, 0xffff0000, v191
	v_lshlrev_b32_e32 v182, 16, v244
	v_and_b32_e32 v183, 0xffff0000, v244
	v_lshlrev_b32_e32 v184, 16, v245
	v_and_b32_e32 v185, 0xffff0000, v245
	v_lshlrev_b32_e32 v178, 16, v246
	v_and_b32_e32 v179, 0xffff0000, v246
	v_lshlrev_b32_e32 v180, 16, v247
	v_and_b32_e32 v181, 0xffff0000, v247
; DI unsigned cvt_pk(float lo, float hi) { unsigned r; asm("v_cvt_pk_bf16_f32 %0, %1, %2" : "=v"(r) : "v"(lo), "v"(hi)); return r; }
;     __device__ __forceinline__ void operator()(const f32x4 (&acc)[2][2][4][2], const Unit& u, int wr, int wc, int fr, int fq) const {
;     ...
;                 for (int mm = 0; mm < 2; ++mm) {
;                     const int m = mp * 2 + mm;
;                     const int row = row0 + ai * HALF + m * 16;
;                     float s = 0.f;
; #pragma unroll
;                     for (int bj = 0; bj < 2; ++bj) {
;                         u32x4* px = (u32x4*)(X + (size_t)row * DM + col0 + bj * HALF);
;                         float xo[8]; unpack8(xin[mm][bj], xo);
;                         const f32x4 a0 = acc[ai][bj][m][0] + pv[mm][bj][0], a1 = acc[ai][bj][m][1] + pv[mm][bj][1];
;                         u32x4 w;
;                         w.x = cvt_pk(xo[0] + scale * a0[0], xo[1] + scale * a0[1]); w.y = cvt_pk(xo[2] + scale * a0[2], xo[3] + scale * a0[3]);
;                         w.z = cvt_pk(xo[4] + scale * a1[0], xo[5] + scale * a1[1]); w.w = cvt_pk(xo[6] + scale * a1[2], xo[7] + scale * a1[3]);
;                         *px = w;
;                         float xn[8]; unpack8(w, xn);
; #pragma unroll
;                         for (int j = 0; j < 8; ++j) s += xn[j] * xn[j];
;                     }
;                     s += __shfl_xor(s, 16); s += __shfl_xor(s, 32);
;                     if (fq == 0) unsafeAtomicAdd(ssn + row, s);
.LBB0_1173:
	s_or_b64 exec, exec, s[16:17]
	s_waitcnt vmcnt(3)
	s_and_saveexec_b64 s[16:17], s[12:13]
	v_lshl_add_u64 v[252:253], v[166:167], 2, s[4:5]
	global_atomic_add_f32 v[252:253], v250, off offset:128
	global_atomic_add_f32 v[252:253], v251, off offset:192
	s_or_b64 exec, exec, s[16:17]
	v_lshlrev_b32_e32 v214, 16, v140
	v_and_b32_e32 v215, 0xffff0000, v140
	v_lshlrev_b32_e32 v244, 16, v141
	v_and_b32_e32 v245, 0xffff0000, v141
	v_pk_add_f32 v[140:141], v[60:61], v[208:209]
	v_lshlrev_b32_e32 v246, 16, v142
	v_and_b32_e32 v247, 0xffff0000, v142
	v_lshlrev_b32_e32 v248, 16, v143
	v_and_b32_e32 v249, 0xffff0000, v143
	v_pk_add_f32 v[142:143], v[62:63], v[210:211]
	v_add_f32_e32 v140, v140, v214
	v_add_f32_e32 v141, v141, v215
	v_pk_add_f32 v[204:205], v[56:57], v[204:205]
	v_cvt_pk_bf16_f32 v140, v140, v141
	v_add_f32_e32 v141, v142, v244
	v_add_f32_e32 v142, v143, v245
	v_pk_add_f32 v[206:207], v[58:59], v[206:207]
	v_cvt_pk_bf16_f32 v141, v141, v142
	v_add_f32_e32 v142, v204, v246
	v_add_f32_e32 v143, v205, v247
	v_cvt_pk_bf16_f32 v142, v142, v143
	v_add_f32_e32 v143, v206, v248
	v_add_f32_e32 v204, v207, v249
	v_and_b32_e32 v205, 0xffff0000, v140
	v_cvt_pk_bf16_f32 v143, v143, v204
	v_lshlrev_b32_e32 v204, 16, v140
	v_mul_f32_e32 v205, v205, v205
	v_lshlrev_b32_e32 v206, 16, v141
	v_fmac_f32_e32 v205, v204, v204
	v_and_b32_e32 v207, 0xffff0000, v141
	v_fmac_f32_e32 v205, v206, v206
	v_lshlrev_b32_e32 v208, 16, v142
	v_fmac_f32_e32 v205, v207, v207
	v_and_b32_e32 v209, 0xffff0000, v142
	v_fmac_f32_e32 v205, v208, v208
	v_lshlrev_b32_e32 v210, 16, v143
	v_fmac_f32_e32 v205, v209, v209
	v_and_b32_e32 v211, 0xffff0000, v143
	v_fmac_f32_e32 v205, v210, v210
	s_waitcnt vmcnt(4)
	v_lshlrev_b32_e32 v204, 16, v136
	v_and_b32_e32 v206, 0xffff0000, v136
	v_lshlrev_b32_e32 v207, 16, v137
	v_and_b32_e32 v208, 0xffff0000, v137
	v_pk_add_f32 v[136:137], v[30:31], v[202:203]
	v_fmac_f32_e32 v205, v211, v211
	v_lshlrev_b32_e32 v209, 16, v138
	v_and_b32_e32 v210, 0xffff0000, v138
	v_lshlrev_b32_e32 v211, 16, v139
	v_and_b32_e32 v214, 0xffff0000, v139
	v_pk_add_f32 v[138:139], v[28:29], v[200:201]
	v_pk_add_f32 v[200:201], v[26:27], v[198:199]
	v_pk_add_f32 v[198:199], v[24:25], v[196:197]
	v_add_f32_e32 v136, v136, v207
	v_add_f32_e32 v137, v137, v208
	v_cvt_pk_bf16_f32 v197, v136, v137
	v_add_f32_e32 v136, v198, v209
	v_add_f32_e32 v137, v199, v210
	v_cvt_pk_bf16_f32 v198, v136, v137
	v_add_f32_e32 v136, v200, v211
	v_add_f32_e32 v138, v138, v204
	v_add_f32_e32 v139, v139, v206
	v_cvt_pk_bf16_f32 v196, v138, v139
	v_add_f32_e32 v137, v201, v214
	v_cvt_pk_bf16_f32 v199, v136, v137
	v_lshlrev_b32_e32 v136, 16, v196
	v_and_b32_e32 v137, 0xffff0000, v196
	v_fmac_f32_e32 v205, v136, v136
	v_lshlrev_b32_e32 v138, 16, v197
	v_fmac_f32_e32 v205, v137, v137
	v_and_b32_e32 v139, 0xffff0000, v197
	v_fmac_f32_e32 v205, v138, v138
	v_lshlrev_b32_e32 v200, 16, v198
	v_fmac_f32_e32 v205, v139, v139
	v_and_b32_e32 v201, 0xffff0000, v198
	v_fmac_f32_e32 v205, v200, v200
	v_lshlrev_b32_e32 v202, 16, v199
	v_fmac_f32_e32 v205, v201, v201
	v_and_b32_e32 v203, 0xffff0000, v199
	v_fmac_f32_e32 v205, v202, v202
	v_fmac_f32_e32 v205, v203, v203
	ds_bpermute_b32 v136, v237, v205
	v_lshl_add_u64 v[138:139], s[36:37], 0, v[186:187]
	v_lshl_add_u64 v[138:139], v[168:169], 1, v[138:139]
	global_store_dwordx4 v[138:139], v[140:143], off
	global_store_dwordx4 v[138:139], v[196:199], off offset:256
	s_waitcnt lgkmcnt(0)
	v_add_f32_e32 v136, v205, v136
	ds_bpermute_b32 v137, v238, v136
	s_waitcnt lgkmcnt(0)
	v_add_f32_e32 v250, v136, v137
.LBB0_1175:
	s_waitcnt vmcnt(5)
	v_lshlrev_b32_e32 v140, 16, v132
	v_and_b32_e32 v141, 0xffff0000, v132
	v_lshlrev_b32_e32 v142, 16, v133
	v_and_b32_e32 v143, 0xffff0000, v133
	v_pk_add_f32 v[132:133], v[52:53], v[192:193]
	v_lshlrev_b32_e32 v186, 16, v134
	v_and_b32_e32 v187, 0xffff0000, v134
	v_lshlrev_b32_e32 v196, 16, v135
	v_and_b32_e32 v197, 0xffff0000, v135
	v_pk_add_f32 v[134:135], v[54:55], v[194:195]
	v_add_f32_e32 v132, v132, v140
	v_add_f32_e32 v133, v133, v141
	v_pk_add_f32 v[138:139], v[48:49], v[188:189]
	v_cvt_pk_bf16_f32 v132, v132, v133
	v_add_f32_e32 v133, v134, v142
	v_add_f32_e32 v134, v135, v143
	s_waitcnt lgkmcnt(0)
	v_pk_add_f32 v[136:137], v[50:51], v[190:191]
	v_cvt_pk_bf16_f32 v133, v133, v134
	v_add_f32_e32 v134, v138, v186
	v_add_f32_e32 v135, v139, v187
	v_cvt_pk_bf16_f32 v134, v134, v135
	v_add_f32_e32 v135, v136, v196
	v_add_f32_e32 v136, v137, v197
	v_and_b32_e32 v137, 0xffff0000, v132
	v_cvt_pk_bf16_f32 v135, v135, v136
	v_lshlrev_b32_e32 v136, 16, v132
	v_mul_f32_e32 v186, v137, v137
	v_lshlrev_b32_e32 v138, 16, v133
	v_fmac_f32_e32 v186, v136, v136
	v_and_b32_e32 v139, 0xffff0000, v133
	v_fmac_f32_e32 v186, v138, v138
	v_lshlrev_b32_e32 v140, 16, v134
	v_fmac_f32_e32 v186, v139, v139
	v_and_b32_e32 v141, 0xffff0000, v134
	v_fmac_f32_e32 v186, v140, v140
	v_lshlrev_b32_e32 v142, 16, v135
	v_fmac_f32_e32 v186, v141, v141
	v_and_b32_e32 v143, 0xffff0000, v135
	v_fmac_f32_e32 v186, v142, v142
	v_fmac_f32_e32 v186, v143, v143
	s_waitcnt vmcnt(4)
	v_lshlrev_b32_e32 v136, 16, v128
	v_and_b32_e32 v137, 0xffff0000, v128
	v_lshlrev_b32_e32 v142, 16, v129
	v_and_b32_e32 v143, 0xffff0000, v129
	v_pk_add_f32 v[128:129], v[22:23], v[184:185]
	v_lshlrev_b32_e32 v187, 16, v130
	v_and_b32_e32 v188, 0xffff0000, v130
	v_lshlrev_b32_e32 v189, 16, v131
	v_and_b32_e32 v190, 0xffff0000, v131
	v_pk_add_f32 v[130:131], v[20:21], v[182:183]
	v_pk_add_f32 v[138:139], v[16:17], v[178:179]
	v_add_f32_e32 v128, v128, v142
	v_pk_add_f32 v[140:141], v[18:19], v[180:181]
	v_add_f32_e32 v131, v131, v137
	v_add_f32_e32 v129, v129, v143
	v_cvt_pk_bf16_f32 v137, v128, v129
	v_add_f32_e32 v128, v138, v187
	v_add_f32_e32 v129, v139, v188
	v_cvt_pk_bf16_f32 v138, v128, v129
	v_add_f32_e32 v128, v140, v189
	v_add_f32_e32 v130, v130, v136
	v_cvt_pk_bf16_f32 v136, v130, v131
	v_add_f32_e32 v129, v141, v190
	v_cvt_pk_bf16_f32 v139, v128, v129
	v_lshlrev_b32_e32 v128, 16, v136
	v_and_b32_e32 v129, 0xffff0000, v136
	v_fmac_f32_e32 v186, v128, v128
	v_lshlrev_b32_e32 v130, 16, v137
	v_fmac_f32_e32 v186, v129, v129
	v_and_b32_e32 v131, 0xffff0000, v137
	v_fmac_f32_e32 v186, v130, v130
	v_lshlrev_b32_e32 v140, 16, v138
	v_fmac_f32_e32 v186, v131, v131
	v_and_b32_e32 v141, 0xffff0000, v138
	v_fmac_f32_e32 v186, v140, v140
	v_lshlrev_b32_e32 v142, 16, v139
	v_fmac_f32_e32 v186, v141, v141
	v_and_b32_e32 v143, 0xffff0000, v139
	v_fmac_f32_e32 v186, v142, v142
	v_fmac_f32_e32 v186, v143, v143
	ds_bpermute_b32 v128, v237, v186
	v_lshl_add_u64 v[130:131], s[36:37], 0, v[176:177]
	v_lshl_add_u64 v[130:131], v[168:169], 1, v[130:131]
	global_store_dwordx4 v[130:131], v[132:135], off
	global_store_dwordx4 v[130:131], v[136:139], off offset:256
	s_waitcnt lgkmcnt(0)
	v_add_f32_e32 v128, v186, v128
	ds_bpermute_b32 v129, v238, v128
	s_waitcnt lgkmcnt(0)
	v_add_f32_e32 v251, v128, v129
;     __device__ __forceinline__ void operator()(const f32x4 (&acc)[2][2][4][2], const Unit& u, int wr, int wc, int fr, int fq) const {
;     ...
;                 u32x4 xin[2][2];
; #pragma unroll
;                 for (int mm = 0; mm < 2; ++mm)
; #pragma unroll
;                     for (int bj = 0; bj < 2; ++bj) xin[mm][bj] = *(const u32x4*)(X + (size_t)(row0 + ai * HALF + (mp * 2 + mm) * 16) * DM + col0 + bj * HALF);
;                 f32x4 pv[2][2][2];
; #pragma unroll
;                 for (int mm = 0; mm < 2; ++mm)
; #pragma unroll
;                     for (int bj = 0; bj < 2; ++bj)
; #pragma unroll
;                         for (int n = 0; n < 2; ++n) pv[mm][bj][n] = (f32x4){0.f, 0.f, 0.f, 0.f};
;                 if (src) {
;                     u32x4 pc[2][2];
;     ...
;                     asm volatile("global_load_dwordx4 %0, %4, off sc1\n\tglobal_load_dwordx4 %1, %5, off sc1\n\tglobal_load_dwordx4 %2, %6, off sc1\n\tglobal_load_dwordx4 %3, %7, off sc1\n\ts_waitcnt vmcnt(0)"
;                                  : "=&v"(pc[0][0]), "=&v"(pc[0][1]), "=&v"(pc[1][0]), "=&v"(pc[1][1])
;                                  : "v"(src + CI(0, 0)), "v"(src + CI(0, 1)), "v"(src + CI(1, 0)), "v"(src + CI(1, 1))
;                                  : "memory");
;     ...
; #pragma unroll
;                     for (int mm = 0; mm < 2; ++mm)
; #pragma unroll
;                         for (int bj = 0; bj < 2; ++bj) { float f[8]; unpack8(pc[mm][bj], f); pv[mm][bj][0] = (f32x4){f[0], f[1], f[2], f[3]}; pv[mm][bj][1] = (f32x4){f[4], f[5], f[6], f[7]}; }
;                 }
; #pragma unroll
;                 for (int mm = 0; mm < 2; ++mm) {
;                     const int m = mp * 2 + mm;
;                     const int row = row0 + ai * HALF + m * 16;
;                     float s = 0.f;
; #pragma unroll
;                     for (int bj = 0; bj < 2; ++bj) {
;                         u32x4* px = (u32x4*)(X + (size_t)row * DM + col0 + bj * HALF);
;                         float xo[8]; unpack8(xin[mm][bj], xo);
;                         const f32x4 a0 = acc[ai][bj][m][0] + pv[mm][bj][0], a1 = acc[ai][bj][m][1] + pv[mm][bj][1];
;                         u32x4 w;
;                         w.x = cvt_pk(xo[0] + scale * a0[0], xo[1] + scale * a0[1]); w.y = cvt_pk(xo[2] + scale * a0[2], xo[3] + scale * a0[3]);
.LBB0_1177:
	s_mov_b64 s[16:17], 0x50000
	v_lshl_add_u64 v[182:183], v[174:175], 0, s[16:17]
	s_mov_b64 s[16:17], 0x58000
	s_waitcnt lgkmcnt(0)
	v_lshl_add_u64 v[128:129], v[172:173], 0, v[182:183]
	v_lshl_add_u64 v[174:175], v[174:175], 0, s[16:17]
	global_load_dwordx4 v[140:143], v[128:129], off
	global_load_dwordx4 v[136:139], v[128:129], off offset:256
	v_lshl_add_u64 v[128:129], v[172:173], 0, v[174:175]
	global_load_dwordx4 v[132:135], v[128:129], off
	s_nop 0
	global_load_dwordx4 v[128:131], v[128:129], off offset:256
	v_mov_b32_e32 v172, 0
	v_mov_b32_e32 v173, 0
	v_mov_b32_e32 v176, 0
	v_mov_b32_e32 v177, 0
	v_mov_b32_e32 v178, 0
	v_mov_b32_e32 v179, 0
	v_mov_b32_e32 v180, 0
	v_mov_b32_e32 v181, 0
	v_mov_b32_e32 v184, 0
	v_mov_b32_e32 v185, 0
	v_mov_b32_e32 v186, 0
	v_mov_b32_e32 v187, 0
	v_mov_b32_e32 v188, 0
	v_mov_b32_e32 v189, 0
	v_mov_b32_e32 v190, 0
	v_mov_b32_e32 v191, 0
	v_mov_b32_e32 v192, 0
	v_mov_b32_e32 v193, 0
	v_mov_b32_e32 v194, 0
	v_mov_b32_e32 v195, 0
	v_mov_b32_e32 v196, 0
	v_mov_b32_e32 v197, 0
	v_mov_b32_e32 v198, 0
	v_mov_b32_e32 v199, 0
	v_mov_b32_e32 v200, 0
	v_mov_b32_e32 v201, 0
	v_mov_b32_e32 v202, 0
	v_mov_b32_e32 v203, 0
	v_mov_b32_e32 v204, 0
	v_mov_b32_e32 v205, 0
	v_mov_b32_e32 v206, 0
	v_mov_b32_e32 v207, 0
	s_and_saveexec_b64 s[16:17], vcc
	s_cbranch_execz .LBB0_1179
	s_mov_b64 s[38:39], 0x2800
	v_lshl_add_u64 v[180:181], v[170:171], 0, s[38:39]
	s_mov_b64 s[38:39], 0x3800
	v_lshl_add_u64 v[188:189], v[170:171], 0, s[38:39]
	s_mov_b64 s[38:39], 0x2c00
	v_lshl_add_u64 v[190:191], v[170:171], 0, s[38:39]
	s_mov_b64 s[38:39], 0x3c00
	v_lshl_add_u64 v[192:193], v[170:171], 0, s[38:39]
	global_load_dwordx4 v[170:173], v[180:181], off sc1
	global_load_dwordx4 v[176:179], v[188:189], off sc1
	global_load_dwordx4 v[184:187], v[190:191], off sc1
	global_load_dwordx4 v[208:211], v[192:193], off sc1
	s_waitcnt vmcnt(0)
	s_nop 0
	v_lshlrev_b32_e32 v204, 16, v170
	v_and_b32_e32 v205, 0xffff0000, v170
	v_lshlrev_b32_e32 v206, 16, v171
	v_and_b32_e32 v207, 0xffff0000, v171
	v_lshlrev_b32_e32 v200, 16, v172
	v_and_b32_e32 v201, 0xffff0000, v172
	v_lshlrev_b32_e32 v202, 16, v173
	v_and_b32_e32 v203, 0xffff0000, v173
	v_lshlrev_b32_e32 v196, 16, v176
	v_and_b32_e32 v197, 0xffff0000, v176
	v_lshlrev_b32_e32 v198, 16, v177
	v_and_b32_e32 v199, 0xffff0000, v177
	v_lshlrev_b32_e32 v192, 16, v178
	v_and_b32_e32 v193, 0xffff0000, v178
	v_lshlrev_b32_e32 v194, 16, v179
	v_and_b32_e32 v195, 0xffff0000, v179
	v_lshlrev_b32_e32 v188, 16, v184
	v_and_b32_e32 v189, 0xffff0000, v184
	v_lshlrev_b32_e32 v190, 16, v185
	v_and_b32_e32 v191, 0xffff0000, v185
	v_lshlrev_b32_e32 v184, 16, v186
	v_and_b32_e32 v185, 0xffff0000, v186
	v_lshlrev_b32_e32 v186, 16, v187
	v_and_b32_e32 v187, 0xffff0000, v187
	v_lshlrev_b32_e32 v178, 16, v208
	v_and_b32_e32 v179, 0xffff0000, v208
	v_lshlrev_b32_e32 v180, 16, v209
	v_and_b32_e32 v181, 0xffff0000, v209
	v_lshlrev_b32_e32 v172, 16, v210
	v_and_b32_e32 v173, 0xffff0000, v210
	v_lshlrev_b32_e32 v176, 16, v211
	v_and_b32_e32 v177, 0xffff0000, v211
.LBB0_1179:
	s_or_b64 exec, exec, s[16:17]
	s_waitcnt vmcnt(3)
	s_and_saveexec_b64 s[16:17], s[12:13]
	v_lshl_add_u64 v[252:253], v[166:167], 2, s[4:5]
	global_atomic_add_f32 v[252:253], v250, off offset:512
	global_atomic_add_f32 v[252:253], v251, off offset:576
	s_or_b64 exec, exec, s[16:17]
	v_lshlrev_b32_e32 v208, 16, v140
	v_and_b32_e32 v209, 0xffff0000, v140
	v_lshlrev_b32_e32 v210, 16, v141
	v_and_b32_e32 v211, 0xffff0000, v141
	v_pk_add_f32 v[140:141], v[44:45], v[204:205]
	v_lshlrev_b32_e32 v214, 16, v142
	v_and_b32_e32 v215, 0xffff0000, v142
	v_lshlrev_b32_e32 v244, 16, v143
	v_and_b32_e32 v245, 0xffff0000, v143
	v_pk_add_f32 v[142:143], v[46:47], v[206:207]
	v_add_f32_e32 v140, v140, v208
	v_add_f32_e32 v141, v141, v209
	v_pk_add_f32 v[200:201], v[40:41], v[200:201]
	v_cvt_pk_bf16_f32 v140, v140, v141
	v_add_f32_e32 v141, v142, v210
	v_add_f32_e32 v142, v143, v211
	v_pk_add_f32 v[170:171], v[42:43], v[202:203]
	v_cvt_pk_bf16_f32 v141, v141, v142
	v_add_f32_e32 v142, v200, v214
	v_add_f32_e32 v143, v201, v215
	v_cvt_pk_bf16_f32 v142, v142, v143
	v_add_f32_e32 v143, v170, v244
	v_add_f32_e32 v170, v171, v245
	v_and_b32_e32 v171, 0xffff0000, v140
	v_cvt_pk_bf16_f32 v143, v143, v170
	v_lshlrev_b32_e32 v170, 16, v140
	v_mul_f32_e32 v206, v171, v171
	v_lshlrev_b32_e32 v200, 16, v141
	v_fmac_f32_e32 v206, v170, v170
	v_and_b32_e32 v201, 0xffff0000, v141
	v_fmac_f32_e32 v206, v200, v200
	v_lshlrev_b32_e32 v202, 16, v142
	v_fmac_f32_e32 v206, v201, v201
	v_and_b32_e32 v203, 0xffff0000, v142
	v_fmac_f32_e32 v206, v202, v202
	v_lshlrev_b32_e32 v204, 16, v143
	v_fmac_f32_e32 v206, v203, v203
	s_waitcnt vmcnt(4)
	v_lshlrev_b32_e32 v200, 16, v136
	v_and_b32_e32 v201, 0xffff0000, v136
	v_lshlrev_b32_e32 v202, 16, v137
	v_and_b32_e32 v203, 0xffff0000, v137
	v_pk_add_f32 v[136:137], v[14:15], v[198:199]
	v_and_b32_e32 v205, 0xffff0000, v143
	v_fmac_f32_e32 v206, v204, v204
	v_lshlrev_b32_e32 v204, 16, v138
	v_pk_add_f32 v[170:171], v[10:11], v[194:195]
	v_pk_add_f32 v[194:195], v[8:9], v[192:193]
	v_add_f32_e32 v136, v136, v202
	v_fmac_f32_e32 v206, v205, v205
	v_and_b32_e32 v205, 0xffff0000, v138
	v_lshlrev_b32_e32 v207, 16, v139
	v_add_f32_e32 v137, v137, v203
	v_cvt_pk_bf16_f32 v193, v136, v137
	v_add_f32_e32 v136, v194, v204
	v_and_b32_e32 v208, 0xffff0000, v139
	v_pk_add_f32 v[138:139], v[12:13], v[196:197]
	v_add_f32_e32 v137, v195, v205
	v_cvt_pk_bf16_f32 v194, v136, v137
	v_add_f32_e32 v136, v170, v207
	v_add_f32_e32 v138, v138, v200
	v_add_f32_e32 v139, v139, v201
	v_cvt_pk_bf16_f32 v192, v138, v139
	v_add_f32_e32 v137, v171, v208
	v_cvt_pk_bf16_f32 v195, v136, v137
	v_lshlrev_b32_e32 v136, 16, v192
	v_and_b32_e32 v137, 0xffff0000, v192
	v_fmac_f32_e32 v206, v136, v136
	v_lshlrev_b32_e32 v138, 16, v193
	v_fmac_f32_e32 v206, v137, v137
	v_and_b32_e32 v139, 0xffff0000, v193
	v_fmac_f32_e32 v206, v138, v138
	v_lshlrev_b32_e32 v170, 16, v194
	v_fmac_f32_e32 v206, v139, v139
	v_and_b32_e32 v171, 0xffff0000, v194
	v_fmac_f32_e32 v206, v170, v170
	v_lshlrev_b32_e32 v196, 16, v195
	v_fmac_f32_e32 v206, v171, v171
	v_and_b32_e32 v197, 0xffff0000, v195
	v_fmac_f32_e32 v206, v196, v196
	v_fmac_f32_e32 v206, v197, v197
	ds_bpermute_b32 v136, v237, v206
	v_lshl_add_u64 v[138:139], s[36:37], 0, v[182:183]
	v_lshl_add_u64 v[138:139], v[168:169], 1, v[138:139]
	global_store_dwordx4 v[138:139], v[140:143], off
	global_store_dwordx4 v[138:139], v[192:195], off offset:256
	s_waitcnt lgkmcnt(0)
	v_add_f32_e32 v136, v206, v136
	ds_bpermute_b32 v137, v238, v136
	s_and_saveexec_b64 s[16:17], s[12:13]
	s_cbranch_execz .LBB0_1181
	s_waitcnt lgkmcnt(0)
	v_add_f32_e32 v138, v136, v137
	v_lshl_add_u64 v[136:137], v[166:167], 2, s[4:5]
	global_atomic_add_f32 v[136:137], v138, off offset:640
; DI unsigned cvt_pk(float lo, float hi) { unsigned r; asm("v_cvt_pk_bf16_f32 %0, %1, %2" : "=v"(r) : "v"(lo), "v"(hi)); return r; }
;     __device__ __forceinline__ void operator()(const f32x4 (&acc)[2][2][4][2], const Unit& u, int wr, int wc, int fr, int fq) const {
;     ...
;                 for (int mm = 0; mm < 2; ++mm) {
;                     const int m = mp * 2 + mm;
;                     const int row = row0 + ai * HALF + m * 16;
;                     float s = 0.f;
; #pragma unroll
;                     for (int bj = 0; bj < 2; ++bj) {
;                         u32x4* px = (u32x4*)(X + (size_t)row * DM + col0 + bj * HALF);
;                         float xo[8]; unpack8(xin[mm][bj], xo);
;                         const f32x4 a0 = acc[ai][bj][m][0] + pv[mm][bj][0], a1 = acc[ai][bj][m][1] + pv[mm][bj][1];
;                         u32x4 w;
;                         w.x = cvt_pk(xo[0] + scale * a0[0], xo[1] + scale * a0[1]); w.y = cvt_pk(xo[2] + scale * a0[2], xo[3] + scale * a0[3]);
;                         w.z = cvt_pk(xo[4] + scale * a1[0], xo[5] + scale * a1[1]); w.w = cvt_pk(xo[6] + scale * a1[2], xo[7] + scale * a1[3]);
;                         *px = w;
;                         float xn[8]; unpack8(w, xn);
; #pragma unroll
;                         for (int j = 0; j < 8; ++j) s += xn[j] * xn[j];
;                     }
;                     s += __shfl_xor(s, 16); s += __shfl_xor(s, 32);
;                     if (fq == 0) unsafeAtomicAdd(ssn + row, s);
.LBB0_1181:
	s_or_b64 exec, exec, s[16:17]
	s_waitcnt vmcnt(5)
	v_lshlrev_b32_e32 v140, 16, v132
	v_and_b32_e32 v141, 0xffff0000, v132
	v_lshlrev_b32_e32 v142, 16, v133
	v_and_b32_e32 v143, 0xffff0000, v133
	v_pk_add_f32 v[132:133], v[36:37], v[188:189]
	v_lshlrev_b32_e32 v170, 16, v134
	v_and_b32_e32 v171, 0xffff0000, v134
	v_lshlrev_b32_e32 v182, 16, v135
	v_and_b32_e32 v183, 0xffff0000, v135
	v_pk_add_f32 v[134:135], v[38:39], v[190:191]
	v_add_f32_e32 v132, v132, v140
	v_add_f32_e32 v133, v133, v141
	v_pk_add_f32 v[138:139], v[32:33], v[184:185]
	v_cvt_pk_bf16_f32 v132, v132, v133
	v_add_f32_e32 v133, v134, v142
	v_add_f32_e32 v134, v135, v143
	s_waitcnt lgkmcnt(0)
	v_pk_add_f32 v[136:137], v[34:35], v[186:187]
	v_cvt_pk_bf16_f32 v133, v133, v134
	v_add_f32_e32 v134, v138, v170
	v_add_f32_e32 v135, v139, v171
	v_cvt_pk_bf16_f32 v134, v134, v135
	v_add_f32_e32 v135, v136, v182
	v_add_f32_e32 v136, v137, v183
	v_and_b32_e32 v137, 0xffff0000, v132
	v_cvt_pk_bf16_f32 v135, v135, v136
	v_lshlrev_b32_e32 v136, 16, v132
	v_mul_f32_e32 v170, v137, v137
	v_lshlrev_b32_e32 v138, 16, v133
	v_fmac_f32_e32 v170, v136, v136
	v_and_b32_e32 v139, 0xffff0000, v133
	v_fmac_f32_e32 v170, v138, v138
	v_lshlrev_b32_e32 v140, 16, v134
	v_fmac_f32_e32 v170, v139, v139
	v_and_b32_e32 v141, 0xffff0000, v134
	v_fmac_f32_e32 v170, v140, v140
	v_lshlrev_b32_e32 v142, 16, v135
	v_fmac_f32_e32 v170, v141, v141
	v_and_b32_e32 v143, 0xffff0000, v135
	v_fmac_f32_e32 v170, v142, v142
	v_fmac_f32_e32 v170, v143, v143
	s_waitcnt vmcnt(4)
	v_lshlrev_b32_e32 v136, 16, v128
	v_and_b32_e32 v137, 0xffff0000, v128
	v_lshlrev_b32_e32 v142, 16, v129
	v_and_b32_e32 v143, 0xffff0000, v129
	v_pk_add_f32 v[128:129], v[6:7], v[180:181]
	v_lshlrev_b32_e32 v171, 16, v130
	v_and_b32_e32 v182, 0xffff0000, v130
	v_lshlrev_b32_e32 v183, 16, v131
	v_and_b32_e32 v184, 0xffff0000, v131
	v_pk_add_f32 v[130:131], v[4:5], v[178:179]
	v_pk_add_f32 v[138:139], v[0:1], v[172:173]
	v_add_f32_e32 v128, v128, v142
	v_pk_add_f32 v[140:141], v[2:3], v[176:177]
	v_add_f32_e32 v131, v131, v137
	v_add_f32_e32 v129, v129, v143
	v_cvt_pk_bf16_f32 v137, v128, v129
	v_add_f32_e32 v128, v138, v171
	v_add_f32_e32 v129, v139, v182
	v_cvt_pk_bf16_f32 v138, v128, v129
	v_add_f32_e32 v128, v140, v183
	v_add_f32_e32 v130, v130, v136
	v_cvt_pk_bf16_f32 v136, v130, v131
	v_add_f32_e32 v129, v141, v184
	v_cvt_pk_bf16_f32 v139, v128, v129
	v_lshlrev_b32_e32 v128, 16, v136
	v_and_b32_e32 v129, 0xffff0000, v136
	v_fmac_f32_e32 v170, v128, v128
	v_lshlrev_b32_e32 v130, 16, v137
	v_fmac_f32_e32 v170, v129, v129
	v_and_b32_e32 v131, 0xffff0000, v137
	v_fmac_f32_e32 v170, v130, v130
	v_lshlrev_b32_e32 v140, 16, v138
	v_fmac_f32_e32 v170, v131, v131
	v_and_b32_e32 v141, 0xffff0000, v138
	v_fmac_f32_e32 v170, v140, v140
	v_lshlrev_b32_e32 v142, 16, v139
	v_fmac_f32_e32 v170, v141, v141
	v_and_b32_e32 v143, 0xffff0000, v139
	v_fmac_f32_e32 v170, v142, v142
	v_fmac_f32_e32 v170, v143, v143
	ds_bpermute_b32 v128, v237, v170
	v_lshl_add_u64 v[130:131], s[36:37], 0, v[174:175]
	v_lshl_add_u64 v[130:131], v[168:169], 1, v[130:131]
	global_store_dwordx4 v[130:131], v[132:135], off
	global_store_dwordx4 v[130:131], v[136:139], off offset:256
	s_waitcnt lgkmcnt(0)
	v_add_f32_e32 v128, v170, v128
	ds_bpermute_b32 v129, v238, v128
	s_and_saveexec_b64 s[16:17], s[12:13]
	s_cbranch_execz .LBB0_1183
	s_waitcnt lgkmcnt(0)
	v_add_f32_e32 v130, v128, v129
	v_lshl_add_u64 v[128:129], v[166:167], 2, s[4:5]
	global_atomic_add_f32 v[128:129], v130, off offset:704

; DI unsigned cvt_pk(float lo, float hi) { unsigned r; asm("v_cvt_pk_bf16_f32 %0, %1, %2" : "=v"(r) : "v"(lo), "v"(hi)); return r; }
;     __device__ __forceinline__ void operator()(const f32x4 (&acc)[2][2][4][2], const Unit& u, int wr, int wc, int fr, int fq) const {
;     ...
;                 for (int mm = 0; mm < 2; ++mm) {
;                     const int m = mp * 2 + mm;
;                     const int row = row0 + ai * HALF + m * 16;
;                     float s = 0.f;
; #pragma unroll
;                     for (int bj = 0; bj < 2; ++bj) {
;                         u32x4* px = (u32x4*)(X + (size_t)row * DM + col0 + bj * HALF);
;                         float xo[8]; unpack8(xin[mm][bj], xo);
;                         const f32x4 a0 = acc[ai][bj][m][0] + pv[mm][bj][0], a1 = acc[ai][bj][m][1] + pv[mm][bj][1];
;                         u32x4 w;
;                         w.x = cvt_pk(xo[0] + scale * a0[0], xo[1] + scale * a0[1]); w.y = cvt_pk(xo[2] + scale * a0[2], xo[3] + scale * a0[3]);
;                         w.z = cvt_pk(xo[4] + scale * a1[0], xo[5] + scale * a1[1]); w.w = cvt_pk(xo[6] + scale * a1[2], xo[7] + scale * a1[3]);
;                         *px = w;
;                         float xn[8]; unpack8(w, xn);
; #pragma unroll
;                         for (int j = 0; j < 8; ++j) s += xn[j] * xn[j];
;                     }
;                     s += __shfl_xor(s, 16); s += __shfl_xor(s, 32);
;                     if (fq == 0) unsafeAtomicAdd(ssn + row, s);
.LBB0_1412:
	s_or_b64 exec, exec, s[12:13]
	s_waitcnt vmcnt(3)
	s_and_saveexec_b64 s[12:13], s[8:9]
	v_lshl_add_u64 v[252:253], v[166:167], 2, s[14:15]
	global_atomic_add_f32 v[252:253], v250, off
	global_atomic_add_f32 v[252:253], v251, off offset:64
	s_or_b64 exec, exec, s[12:13]
	v_lshlrev_b32_e32 v214, 16, v140
	v_and_b32_e32 v215, 0xffff0000, v140
	v_lshlrev_b32_e32 v244, 16, v141
	v_and_b32_e32 v245, 0xffff0000, v141
	v_and_b32_e32 v247, 0xffff0000, v142
	v_pk_add_f32 v[140:141], v[108:109], v[208:209]
	v_pk_add_f32 v[204:205], v[104:105], v[204:205]
	v_lshlrev_b32_e32 v246, 16, v142
	v_fmac_f32_e32 v214, 0.5, v140
	v_fmac_f32_e32 v215, 0.5, v141
	v_cvt_pk_bf16_f32 v140, v214, v215
	v_fmac_f32_e32 v247, 0.5, v205
	v_and_b32_e32 v205, 0xffff0000, v140
	v_lshlrev_b32_e32 v248, 16, v143
	v_and_b32_e32 v249, 0xffff0000, v143
	v_pk_add_f32 v[142:143], v[110:111], v[210:211]
	v_pk_add_f32 v[206:207], v[106:107], v[206:207]
	v_fmac_f32_e32 v246, 0.5, v204
	v_lshlrev_b32_e32 v204, 16, v140
	v_mul_f32_e32 v205, v205, v205
	v_fmac_f32_e32 v244, 0.5, v142
	v_fmac_f32_e32 v245, 0.5, v143
	v_cvt_pk_bf16_f32 v141, v244, v245
	v_fmac_f32_e32 v248, 0.5, v206
	v_lshlrev_b32_e32 v206, 16, v141
	v_fmac_f32_e32 v205, v204, v204
	v_fmac_f32_e32 v249, 0.5, v207
	v_and_b32_e32 v207, 0xffff0000, v141
	v_fmac_f32_e32 v205, v206, v206
	v_cvt_pk_bf16_f32 v142, v246, v247
	v_fmac_f32_e32 v205, v207, v207
	v_lshlrev_b32_e32 v208, 16, v142
	v_and_b32_e32 v209, 0xffff0000, v142
	v_fmac_f32_e32 v205, v208, v208
	v_cvt_pk_bf16_f32 v143, v248, v249
	v_fmac_f32_e32 v205, v209, v209
	v_lshlrev_b32_e32 v210, 16, v143
	v_and_b32_e32 v211, 0xffff0000, v143
	v_fmac_f32_e32 v205, v210, v210
	v_fmac_f32_e32 v205, v211, v211
	s_waitcnt vmcnt(4)
	v_lshlrev_b32_e32 v204, 16, v136
	v_and_b32_e32 v206, 0xffff0000, v136
	v_lshlrev_b32_e32 v207, 16, v137
	v_and_b32_e32 v208, 0xffff0000, v137
	v_lshlrev_b32_e32 v209, 16, v138
	v_and_b32_e32 v210, 0xffff0000, v138
	v_lshlrev_b32_e32 v211, 16, v139
	v_and_b32_e32 v214, 0xffff0000, v139
	v_pk_add_f32 v[136:137], v[78:79], v[202:203]
	v_pk_add_f32 v[138:139], v[76:77], v[200:201]
	v_pk_add_f32 v[200:201], v[74:75], v[198:199]
	v_pk_add_f32 v[198:199], v[72:73], v[196:197]
	v_fmac_f32_e32 v204, 0.5, v138
	v_fmac_f32_e32 v206, 0.5, v139
	v_cvt_pk_bf16_f32 v196, v204, v206
	v_fmac_f32_e32 v207, 0.5, v136
	v_lshlrev_b32_e32 v136, 16, v196
	v_fmac_f32_e32 v208, 0.5, v137
	v_and_b32_e32 v137, 0xffff0000, v196
	v_fmac_f32_e32 v205, v136, v136
	v_cvt_pk_bf16_f32 v197, v207, v208
	v_fmac_f32_e32 v205, v137, v137
	v_lshlrev_b32_e32 v138, 16, v197
	v_and_b32_e32 v139, 0xffff0000, v197
	v_fmac_f32_e32 v205, v138, v138
	v_fmac_f32_e32 v209, 0.5, v198
	v_fmac_f32_e32 v210, 0.5, v199
	v_cvt_pk_bf16_f32 v198, v209, v210
	v_fmac_f32_e32 v211, 0.5, v200
	v_lshlrev_b32_e32 v200, 16, v198
	v_fmac_f32_e32 v205, v139, v139
	v_fmac_f32_e32 v214, 0.5, v201
	v_and_b32_e32 v201, 0xffff0000, v198
	v_fmac_f32_e32 v205, v200, v200
	v_cvt_pk_bf16_f32 v199, v211, v214
	v_fmac_f32_e32 v205, v201, v201
	v_lshlrev_b32_e32 v202, 16, v199
	v_and_b32_e32 v203, 0xffff0000, v199
	v_fmac_f32_e32 v205, v202, v202
	v_fmac_f32_e32 v205, v203, v203
	ds_bpermute_b32 v136, v237, v205
	v_lshl_add_u64 v[138:139], s[28:29], 0, v[186:187]
	v_lshl_add_u64 v[138:139], v[168:169], 1, v[138:139]
	global_store_dwordx4 v[138:139], v[140:143], off
	global_store_dwordx4 v[138:139], v[196:199], off offset:256
	s_waitcnt lgkmcnt(0)
	v_add_f32_e32 v136, v205, v136
	ds_bpermute_b32 v137, v238, v136
	s_waitcnt lgkmcnt(0)
	v_add_f32_e32 v250, v136, v137

; DI unsigned cvt_pk(float lo, float hi) { unsigned r; asm("v_cvt_pk_bf16_f32 %0, %1, %2" : "=v"(r) : "v"(lo), "v"(hi)); return r; }
;     __device__ __forceinline__ void operator()(const f32x4 (&acc)[2][2][4][2], const Unit& u, int wr, int wc, int fr, int fq) const {
;     ...
;                 for (int mm = 0; mm < 2; ++mm) {
;                     const int m = mp * 2 + mm;
;                     const int row = row0 + ai * HALF + m * 16;
;                     float s = 0.f;
; #pragma unroll
;                     for (int bj = 0; bj < 2; ++bj) {
;                         u32x4* px = (u32x4*)(X + (size_t)row * DM + col0 + bj * HALF);
;                         float xo[8]; unpack8(xin[mm][bj], xo);
;                         const f32x4 a0 = acc[ai][bj][m][0] + pv[mm][bj][0], a1 = acc[ai][bj][m][1] + pv[mm][bj][1];
;                         u32x4 w;
;                         w.x = cvt_pk(xo[0] + scale * a0[0], xo[1] + scale * a0[1]); w.y = cvt_pk(xo[2] + scale * a0[2], xo[3] + scale * a0[3]);
;                         w.z = cvt_pk(xo[4] + scale * a1[0], xo[5] + scale * a1[1]); w.w = cvt_pk(xo[6] + scale * a1[2], xo[7] + scale * a1[3]);
;                         *px = w;
;                         float xn[8]; unpack8(w, xn);
; #pragma unroll
;                         for (int j = 0; j < 8; ++j) s += xn[j] * xn[j];
;                     }
;                     s += __shfl_xor(s, 16); s += __shfl_xor(s, 32);
;                     if (fq == 0) unsafeAtomicAdd(ssn + row, s);
.LBB0_1418:
	s_or_b64 exec, exec, s[12:13]
	s_waitcnt vmcnt(3)
	s_and_saveexec_b64 s[12:13], s[8:9]
	v_lshl_add_u64 v[252:253], v[166:167], 2, s[14:15]
	global_atomic_add_f32 v[252:253], v250, off offset:128
	global_atomic_add_f32 v[252:253], v251, off offset:192
	s_or_b64 exec, exec, s[12:13]
	v_lshlrev_b32_e32 v214, 16, v140
	v_and_b32_e32 v215, 0xffff0000, v140
	v_lshlrev_b32_e32 v244, 16, v141
	v_and_b32_e32 v245, 0xffff0000, v141
	v_and_b32_e32 v247, 0xffff0000, v142
	v_pk_add_f32 v[140:141], v[60:61], v[208:209]
	v_pk_add_f32 v[204:205], v[56:57], v[204:205]
	v_lshlrev_b32_e32 v246, 16, v142
	v_fmac_f32_e32 v214, 0.5, v140
	v_fmac_f32_e32 v215, 0.5, v141
	v_cvt_pk_bf16_f32 v140, v214, v215
	v_fmac_f32_e32 v247, 0.5, v205
	v_and_b32_e32 v205, 0xffff0000, v140
	v_lshlrev_b32_e32 v248, 16, v143
	v_and_b32_e32 v249, 0xffff0000, v143
	v_pk_add_f32 v[142:143], v[62:63], v[210:211]
	v_pk_add_f32 v[206:207], v[58:59], v[206:207]
	v_fmac_f32_e32 v246, 0.5, v204
	v_lshlrev_b32_e32 v204, 16, v140
	v_mul_f32_e32 v205, v205, v205
	v_fmac_f32_e32 v244, 0.5, v142
	v_fmac_f32_e32 v245, 0.5, v143
	v_cvt_pk_bf16_f32 v141, v244, v245
	v_fmac_f32_e32 v248, 0.5, v206
	v_lshlrev_b32_e32 v206, 16, v141
	v_fmac_f32_e32 v205, v204, v204
	v_fmac_f32_e32 v249, 0.5, v207
	v_and_b32_e32 v207, 0xffff0000, v141
	v_fmac_f32_e32 v205, v206, v206
	v_cvt_pk_bf16_f32 v142, v246, v247
	v_fmac_f32_e32 v205, v207, v207
	v_lshlrev_b32_e32 v208, 16, v142
	v_and_b32_e32 v209, 0xffff0000, v142
	v_fmac_f32_e32 v205, v208, v208
	v_cvt_pk_bf16_f32 v143, v248, v249
	v_fmac_f32_e32 v205, v209, v209
	v_lshlrev_b32_e32 v210, 16, v143
	v_and_b32_e32 v211, 0xffff0000, v143
	v_fmac_f32_e32 v205, v210, v210
	v_fmac_f32_e32 v205, v211, v211
	s_waitcnt vmcnt(4)
	v_lshlrev_b32_e32 v204, 16, v136
	v_and_b32_e32 v206, 0xffff0000, v136
	v_lshlrev_b32_e32 v207, 16, v137
	v_and_b32_e32 v208, 0xffff0000, v137
	v_lshlrev_b32_e32 v209, 16, v138
	v_and_b32_e32 v210, 0xffff0000, v138
	v_lshlrev_b32_e32 v211, 16, v139
	v_and_b32_e32 v214, 0xffff0000, v139
	v_pk_add_f32 v[136:137], v[30:31], v[202:203]
	v_pk_add_f32 v[138:139], v[28:29], v[200:201]
	v_pk_add_f32 v[200:201], v[26:27], v[198:199]
	v_pk_add_f32 v[198:199], v[24:25], v[196:197]
	v_fmac_f32_e32 v204, 0.5, v138
	v_fmac_f32_e32 v206, 0.5, v139
	v_cvt_pk_bf16_f32 v196, v204, v206
	v_fmac_f32_e32 v207, 0.5, v136
	v_lshlrev_b32_e32 v136, 16, v196
	v_fmac_f32_e32 v208, 0.5, v137
	v_and_b32_e32 v137, 0xffff0000, v196
	v_fmac_f32_e32 v205, v136, v136
	v_cvt_pk_bf16_f32 v197, v207, v208
	v_fmac_f32_e32 v205, v137, v137
	v_lshlrev_b32_e32 v138, 16, v197
	v_and_b32_e32 v139, 0xffff0000, v197
	v_fmac_f32_e32 v205, v138, v138
	v_fmac_f32_e32 v209, 0.5, v198
	v_fmac_f32_e32 v210, 0.5, v199
	v_cvt_pk_bf16_f32 v198, v209, v210
	v_fmac_f32_e32 v211, 0.5, v200
	v_lshlrev_b32_e32 v200, 16, v198
	v_fmac_f32_e32 v205, v139, v139
	v_fmac_f32_e32 v214, 0.5, v201
	v_and_b32_e32 v201, 0xffff0000, v198
	v_fmac_f32_e32 v205, v200, v200
	v_cvt_pk_bf16_f32 v199, v211, v214
	v_fmac_f32_e32 v205, v201, v201
	v_lshlrev_b32_e32 v202, 16, v199
	v_and_b32_e32 v203, 0xffff0000, v199
	v_fmac_f32_e32 v205, v202, v202
	v_fmac_f32_e32 v205, v203, v203
	ds_bpermute_b32 v136, v237, v205
	v_lshl_add_u64 v[138:139], s[28:29], 0, v[186:187]
	v_lshl_add_u64 v[138:139], v[168:169], 1, v[138:139]
	global_store_dwordx4 v[138:139], v[140:143], off
	global_store_dwordx4 v[138:139], v[196:199], off offset:256
	s_waitcnt lgkmcnt(0)
	v_add_f32_e32 v136, v205, v136
	ds_bpermute_b32 v137, v238, v136
	s_waitcnt lgkmcnt(0)
	v_add_f32_e32 v250, v136, v137

; DI unsigned cvt_pk(float lo, float hi) { unsigned r; asm("v_cvt_pk_bf16_f32 %0, %1, %2" : "=v"(r) : "v"(lo), "v"(hi)); return r; }
;     __device__ __forceinline__ void operator()(const f32x4 (&acc)[2][2][4][2], const Unit& u, int wr, int wc, int fr, int fq) const {
;     ...
;                 for (int mm = 0; mm < 2; ++mm) {
;                     const int m = mp * 2 + mm;
;                     const int row = row0 + ai * HALF + m * 16;
;                     float s = 0.f;
; #pragma unroll
;                     for (int bj = 0; bj < 2; ++bj) {
;                         u32x4* px = (u32x4*)(X + (size_t)row * DM + col0 + bj * HALF);
;                         float xo[8]; unpack8(xin[mm][bj], xo);
;                         const f32x4 a0 = acc[ai][bj][m][0] + pv[mm][bj][0], a1 = acc[ai][bj][m][1] + pv[mm][bj][1];
;                         u32x4 w;
;                         w.x = cvt_pk(xo[0] + scale * a0[0], xo[1] + scale * a0[1]); w.y = cvt_pk(xo[2] + scale * a0[2], xo[3] + scale * a0[3]);
;                         w.z = cvt_pk(xo[4] + scale * a1[0], xo[5] + scale * a1[1]); w.w = cvt_pk(xo[6] + scale * a1[2], xo[7] + scale * a1[3]);
;                         *px = w;
;                         float xn[8]; unpack8(w, xn);
; #pragma unroll
;                         for (int j = 0; j < 8; ++j) s += xn[j] * xn[j];
;                     }
;                     s += __shfl_xor(s, 16); s += __shfl_xor(s, 32);
;                     if (fq == 0) unsafeAtomicAdd(ssn + row, s);
.LBB0_1424:
	s_or_b64 exec, exec, s[12:13]
	s_waitcnt vmcnt(3)
	s_and_saveexec_b64 s[12:13], s[8:9]
	v_lshl_add_u64 v[252:253], v[166:167], 2, s[14:15]
	global_atomic_add_f32 v[252:253], v250, off offset:512
	global_atomic_add_f32 v[252:253], v251, off offset:576
	s_or_b64 exec, exec, s[12:13]
	v_lshlrev_b32_e32 v208, 16, v140
	v_and_b32_e32 v209, 0xffff0000, v140
	v_lshlrev_b32_e32 v210, 16, v141
	v_and_b32_e32 v211, 0xffff0000, v141
	v_and_b32_e32 v245, 0xffff0000, v143
	v_pk_add_f32 v[140:141], v[44:45], v[204:205]
	v_pk_add_f32 v[170:171], v[42:43], v[202:203]
	v_lshlrev_b32_e32 v244, 16, v143
	v_fmac_f32_e32 v208, 0.5, v140
	v_fmac_f32_e32 v209, 0.5, v141
	v_cvt_pk_bf16_f32 v140, v208, v209
	v_fmac_f32_e32 v245, 0.5, v171
	v_and_b32_e32 v171, 0xffff0000, v140
	v_lshlrev_b32_e32 v214, 16, v142
	v_and_b32_e32 v215, 0xffff0000, v142
	v_pk_add_f32 v[142:143], v[46:47], v[206:207]
	v_pk_add_f32 v[200:201], v[40:41], v[200:201]
	v_fmac_f32_e32 v244, 0.5, v170
	v_lshlrev_b32_e32 v170, 16, v140
	v_mul_f32_e32 v206, v171, v171
	v_fmac_f32_e32 v210, 0.5, v142
	v_fmac_f32_e32 v211, 0.5, v143
	v_cvt_pk_bf16_f32 v141, v210, v211
	v_fmac_f32_e32 v214, 0.5, v200
	v_lshlrev_b32_e32 v200, 16, v141
	v_fmac_f32_e32 v206, v170, v170
	v_fmac_f32_e32 v215, 0.5, v201
	v_and_b32_e32 v201, 0xffff0000, v141
	v_fmac_f32_e32 v206, v200, v200
	v_cvt_pk_bf16_f32 v142, v214, v215
	v_fmac_f32_e32 v206, v201, v201
	v_lshlrev_b32_e32 v202, 16, v142
	v_and_b32_e32 v203, 0xffff0000, v142
	v_fmac_f32_e32 v206, v202, v202
	v_cvt_pk_bf16_f32 v143, v244, v245
	v_fmac_f32_e32 v206, v203, v203
	v_lshlrev_b32_e32 v204, 16, v143
	v_and_b32_e32 v205, 0xffff0000, v143
	v_fmac_f32_e32 v206, v204, v204
	v_fmac_f32_e32 v206, v205, v205
	s_waitcnt vmcnt(4)
	v_lshlrev_b32_e32 v200, 16, v136
	v_and_b32_e32 v201, 0xffff0000, v136
	v_lshlrev_b32_e32 v202, 16, v137
	v_and_b32_e32 v203, 0xffff0000, v137
	v_lshlrev_b32_e32 v204, 16, v138
	v_and_b32_e32 v205, 0xffff0000, v138
	v_lshlrev_b32_e32 v207, 16, v139
	v_and_b32_e32 v208, 0xffff0000, v139
	v_pk_add_f32 v[136:137], v[14:15], v[198:199]
	v_pk_add_f32 v[138:139], v[12:13], v[196:197]
	v_pk_add_f32 v[170:171], v[10:11], v[194:195]
	v_pk_add_f32 v[194:195], v[8:9], v[192:193]
	v_fmac_f32_e32 v200, 0.5, v138
	v_fmac_f32_e32 v201, 0.5, v139
	v_cvt_pk_bf16_f32 v192, v200, v201
	v_fmac_f32_e32 v202, 0.5, v136
	v_lshlrev_b32_e32 v136, 16, v192
	v_fmac_f32_e32 v203, 0.5, v137
	v_and_b32_e32 v137, 0xffff0000, v192
	v_fmac_f32_e32 v206, v136, v136
	v_cvt_pk_bf16_f32 v193, v202, v203
	v_fmac_f32_e32 v206, v137, v137
	v_lshlrev_b32_e32 v138, 16, v193
	v_and_b32_e32 v139, 0xffff0000, v193
	v_fmac_f32_e32 v206, v138, v138
	v_fmac_f32_e32 v204, 0.5, v194
	v_fmac_f32_e32 v205, 0.5, v195
	v_cvt_pk_bf16_f32 v194, v204, v205
	v_fmac_f32_e32 v207, 0.5, v170
	v_lshlrev_b32_e32 v170, 16, v194
	v_fmac_f32_e32 v206, v139, v139
	v_fmac_f32_e32 v208, 0.5, v171
	v_and_b32_e32 v171, 0xffff0000, v194
	v_fmac_f32_e32 v206, v170, v170
	v_cvt_pk_bf16_f32 v195, v207, v208
	v_fmac_f32_e32 v206, v171, v171
	v_lshlrev_b32_e32 v196, 16, v195
	v_and_b32_e32 v197, 0xffff0000, v195
	v_fmac_f32_e32 v206, v196, v196
	v_fmac_f32_e32 v206, v197, v197
	ds_bpermute_b32 v136, v237, v206
	v_lshl_add_u64 v[138:139], s[28:29], 0, v[182:183]
	v_lshl_add_u64 v[138:139], v[168:169], 1, v[138:139]
	global_store_dwordx4 v[138:139], v[140:143], off
	global_store_dwordx4 v[138:139], v[192:195], off offset:256
	s_waitcnt lgkmcnt(0)
	v_add_f32_e32 v136, v206, v136
	ds_bpermute_b32 v137, v238, v136
	s_and_saveexec_b64 s[12:13], s[8:9]
	s_cbranch_execz .LBB0_1426
	s_waitcnt lgkmcnt(0)
	v_add_f32_e32 v138, v136, v137
	v_lshl_add_u64 v[136:137], v[166:167], 2, s[14:15]
	global_atomic_add_f32 v[136:137], v138, off offset:640
; DI unsigned cvt_pk(float lo, float hi) { unsigned r; asm("v_cvt_pk_bf16_f32 %0, %1, %2" : "=v"(r) : "v"(lo), "v"(hi)); return r; }
;     __device__ __forceinline__ void operator()(const f32x4 (&acc)[2][2][4][2], const Unit& u, int wr, int wc, int fr, int fq) const {
;     ...
;                 for (int mm = 0; mm < 2; ++mm) {
;                     const int m = mp * 2 + mm;
;                     const int row = row0 + ai * HALF + m * 16;
;                     float s = 0.f;
; #pragma unroll
;                     for (int bj = 0; bj < 2; ++bj) {
;                         u32x4* px = (u32x4*)(X + (size_t)row * DM + col0 + bj * HALF);
;                         float xo[8]; unpack8(xin[mm][bj], xo);
;                         const f32x4 a0 = acc[ai][bj][m][0] + pv[mm][bj][0], a1 = acc[ai][bj][m][1] + pv[mm][bj][1];
;                         u32x4 w;
;                         w.x = cvt_pk(xo[0] + scale * a0[0], xo[1] + scale * a0[1]); w.y = cvt_pk(xo[2] + scale * a0[2], xo[3] + scale * a0[3]);
;                         w.z = cvt_pk(xo[4] + scale * a1[0], xo[5] + scale * a1[1]); w.w = cvt_pk(xo[6] + scale * a1[2], xo[7] + scale * a1[3]);
;                         *px = w;
;                         float xn[8]; unpack8(w, xn);
; #pragma unroll
;                         for (int j = 0; j < 8; ++j) s += xn[j] * xn[j];
;                     }
;                     s += __shfl_xor(s, 16); s += __shfl_xor(s, 32);
;                     if (fq == 0) unsafeAtomicAdd(ssn + row, s);
.LBB0_1426:
	s_or_b64 exec, exec, s[12:13]
	s_waitcnt vmcnt(5)
	v_lshlrev_b32_e32 v140, 16, v132
	v_and_b32_e32 v141, 0xffff0000, v132
	v_lshlrev_b32_e32 v142, 16, v133
	v_and_b32_e32 v143, 0xffff0000, v133
	v_lshlrev_b32_e32 v170, 16, v134
	v_and_b32_e32 v183, 0xffff0000, v135
	v_pk_add_f32 v[132:133], v[36:37], v[188:189]
	s_waitcnt lgkmcnt(0)
	v_pk_add_f32 v[136:137], v[34:35], v[186:187]
	v_pk_add_f32 v[138:139], v[32:33], v[184:185]
	v_and_b32_e32 v171, 0xffff0000, v134
	v_lshlrev_b32_e32 v182, 16, v135
	v_pk_add_f32 v[134:135], v[38:39], v[190:191]
	v_fmac_f32_e32 v140, 0.5, v132
	v_fmac_f32_e32 v141, 0.5, v133
	v_cvt_pk_bf16_f32 v132, v140, v141
	v_fmac_f32_e32 v170, 0.5, v138
	v_fmac_f32_e32 v183, 0.5, v137
	v_and_b32_e32 v137, 0xffff0000, v132
	v_fmac_f32_e32 v142, 0.5, v134
	v_fmac_f32_e32 v171, 0.5, v139
	v_cvt_pk_bf16_f32 v134, v170, v171
	v_fmac_f32_e32 v182, 0.5, v136
	v_lshlrev_b32_e32 v136, 16, v132
	v_mul_f32_e32 v170, v137, v137
	v_fmac_f32_e32 v143, 0.5, v135
	v_cvt_pk_bf16_f32 v133, v142, v143
	v_fmac_f32_e32 v170, v136, v136
	v_lshlrev_b32_e32 v138, 16, v133
	v_and_b32_e32 v139, 0xffff0000, v133
	v_fmac_f32_e32 v170, v138, v138
	v_lshlrev_b32_e32 v140, 16, v134
	v_fmac_f32_e32 v170, v139, v139
	v_and_b32_e32 v141, 0xffff0000, v134
	v_fmac_f32_e32 v170, v140, v140
	v_cvt_pk_bf16_f32 v135, v182, v183
	v_fmac_f32_e32 v170, v141, v141
	v_lshlrev_b32_e32 v142, 16, v135
	v_and_b32_e32 v143, 0xffff0000, v135
	v_fmac_f32_e32 v170, v142, v142
	s_waitcnt vmcnt(4)
	v_lshlrev_b32_e32 v136, 16, v128
	v_lshlrev_b32_e32 v171, 16, v130
	v_and_b32_e32 v182, 0xffff0000, v130
	v_lshlrev_b32_e32 v183, 16, v131
	v_and_b32_e32 v184, 0xffff0000, v131
	v_pk_add_f32 v[130:131], v[4:5], v[178:179]
	v_fmac_f32_e32 v170, v143, v143
	v_and_b32_e32 v137, 0xffff0000, v128
	v_lshlrev_b32_e32 v142, 16, v129
	v_and_b32_e32 v143, 0xffff0000, v129
	v_pk_add_f32 v[128:129], v[6:7], v[180:181]
	v_fmac_f32_e32 v136, 0.5, v130
	v_fmac_f32_e32 v137, 0.5, v131
	v_cvt_pk_bf16_f32 v136, v136, v137
	v_fmac_f32_e32 v142, 0.5, v128
	v_lshlrev_b32_e32 v128, 16, v136
	v_fmac_f32_e32 v143, 0.5, v129
	v_and_b32_e32 v129, 0xffff0000, v136
	v_fmac_f32_e32 v170, v128, v128
	v_cvt_pk_bf16_f32 v137, v142, v143
	v_fmac_f32_e32 v170, v129, v129
	v_lshlrev_b32_e32 v130, 16, v137
	v_pk_add_f32 v[140:141], v[2:3], v[176:177]
	v_pk_add_f32 v[138:139], v[0:1], v[172:173]
	v_and_b32_e32 v131, 0xffff0000, v137
	v_fmac_f32_e32 v170, v130, v130
	v_fmac_f32_e32 v171, 0.5, v138
	v_fmac_f32_e32 v182, 0.5, v139
	v_cvt_pk_bf16_f32 v138, v171, v182
	v_fmac_f32_e32 v183, 0.5, v140
	v_lshlrev_b32_e32 v140, 16, v138
	v_fmac_f32_e32 v170, v131, v131
	v_fmac_f32_e32 v184, 0.5, v141
	v_and_b32_e32 v141, 0xffff0000, v138
	v_fmac_f32_e32 v170, v140, v140
	v_cvt_pk_bf16_f32 v139, v183, v184
	v_fmac_f32_e32 v170, v141, v141
	v_lshlrev_b32_e32 v142, 16, v139
	v_and_b32_e32 v143, 0xffff0000, v139
	v_fmac_f32_e32 v170, v142, v142
	v_fmac_f32_e32 v170, v143, v143
	ds_bpermute_b32 v128, v237, v170
	v_lshl_add_u64 v[130:131], s[28:29], 0, v[174:175]
	v_lshl_add_u64 v[130:131], v[168:169], 1, v[130:131]
	global_store_dwordx4 v[130:131], v[132:135], off
	global_store_dwordx4 v[130:131], v[136:139], off offset:256
	s_waitcnt lgkmcnt(0)
	v_add_f32_e32 v128, v170, v128
	ds_bpermute_b32 v129, v238, v128
	s_and_saveexec_b64 s[12:13], s[8:9]
	s_cbranch_execz .LBB0_1428
	s_waitcnt lgkmcnt(0)
	v_add_f32_e32 v130, v128, v129
	v_lshl_add_u64 v[128:129], v[166:167], 2, s[14:15]
	global_atomic_add_f32 v[128:129], v130, off offset:704
